# v022
# speedup vs baseline: 1.0141x; 1.0047x over previous
; #define PUT(val) *(uint2*)(g_smem + est_off(rl_, cl)) = pack4(val)
; #define STAGED2(WBODY, SBODY) { { constexpr int AIV = 0; (void)AIV; HLOOP(0, WBODY) __syncthreads(); WLOOP(0, SBODY) } __syncthreads(); { constexpr int AIV = 1; (void)AIV; HLOOP(1, WBODY) __syncthreads(); WLOOP(1, SBODY) } }
; __device__ __forceinline__ float gelu_tanh(float x) {
;   float u = 0.7978845608028654f * (x + 0.044715f * x * x * x);
;   float e = __expf(2.f * u);
;   float t = 1.f - 2.f * __builtin_amdgcn_rcpf(e + 1.f);
;   return 0.5f * x * (1.f + t);
; }
; __device__ __forceinline__ void gemm_epi(const Job& J, f32x4 (&acc)[2][2][4][2], int brow, int bcol, int wvs) {
;     ...
;   case E_UPACT: { u16* C = (u16*)J.C; const u16* G = (const u16*)J.aux; const float* cw = (const float*)J.aux2; const float* cb = (const float*)J.aux3; const int lg = J.flag;
;     STAGED2(({ int pos = R & ((1 << lg) - 1); const u16* gp = G + (long)R * DFF + Cc;
;         f32x4 g0 = unpack4(*(const uint2*)gp), gm = {0.f, 0.f, 0.f, 0.f}, gn = {0.f, 0.f, 0.f, 0.f};
;         if (pos > 0) gm = unpack4(*(const uint2*)(gp - DFF));
;         if (pos < (1 << lg) - 1) gn = unpack4(*(const uint2*)(gp + DFF));
;         f32x4 w0 = *(const f32x4*)(cw + Cc), w1 = *(const f32x4*)(cw + DFF + Cc), w2 = *(const f32x4*)(cw + 2 * DFF + Cc), bb = *(const f32x4*)(cb + Cc);
;         f32x4 o; _Pragma("unroll") for (int j = 0; j < 4; ++j) { float cv = gm[j] * w0[j] + g0[j] * w1[j] + gn[j] * w2[j] + bb[j]; o[j] = gelu_tanh(cv) * v[j]; }
;         PUT(o); }), ({ *(u32x4*)(C + (long)R * ldc + Cc) = LDV; })) } break;
.LBB0_516:
	v_mbcnt_lo_u32_b32 v210, -1, 0
	v_mbcnt_hi_u32_b32 v210, -1, v210
	s_mov_b64 s[6:7], -1
	v_add_u32_e32 v213, s69, v210
	v_bfe_u32 v207, v213, 8, 1
	v_bfe_u32 v208, v213, 6, 2
	v_and_b32_e32 v209, 15, v210
	v_lshrrev_b32_e32 v211, 4, v213
	v_bfe_u32 v212, v213, 4, 2
	s_mov_b64 s[52:53], 0
	s_cmp_lt_i32 s91, 5
	s_mov_b64 s[8:9], 0
	s_cbranch_scc1 .LBB0_696
	s_cmp_gt_i32 s91, 6
	s_cbranch_scc0 .LBB0_676
	s_cmp_gt_i32 s91, 8
	s_cbranch_scc0 .LBB0_654
	s_cmp_eq_u32 s91, 9
	s_mov_b64 s[8:9], -1
	s_cbranch_scc0 .LBB0_653
	v_lshlrev_b32_e32 v228, 2, v212
	v_lshl_or_b32 v229, v208, 5, v228
	v_lshl_or_b32 v230, v207, 6, v209
	v_add_u32_e32 v231, s22, v229
	v_add_u32_e32 v224, s90, v230
	v_lshlrev_b32_e32 v220, 2, v231
	v_lshlrev_b32_e32 v231, 1, v231
	s_movk_i32 s42, 0x2c00
	v_mad_u32_u24 v221, v224, s42, v231
	v_lshlrev_b32_e32 v228, 16, v207
	v_lshl_add_u32 v228, v209, 9, v228
	v_and_b32_e32 v231, 1, v212
	v_lshl_add_u32 v228, v231, 3, v228
	v_lshrrev_b32_e32 v231, 1, v212
	v_lshl_or_b32 v231, v208, 2, v231
	v_xor_b32_e32 v231, v231, v209
	v_lshl_add_u32 v222, v231, 4, v228
	v_xor_b32_e32 v231, 2, v231
	v_lshl_add_u32 v223, v231, 4, v228
	s_add_u32 s14, s46, 0xffffd400
	s_addc_u32 s15, s47, -1
	s_add_u32 s16, s46, 0x2c00
	s_addc_u32 s17, s47, 0
	s_add_u32 s18, s12, 0x5800
	s_addc_u32 s19, s13, 0
	s_add_u32 s20, s12, 0xb000
	s_addc_u32 s21, s13, 0
	s_lshl_b32 s31, 1, s95
	s_add_i32 s31, s31, -1
	s_add_i32 s84, s90, 0x80
	s_mov_b32 s96, 0x3dd2d3e7
	s_mov_b32 s97, 0x3dd2d3e7
	v_mov_b32_e32 v232, 0x40135761
	v_mov_b32_e32 v233, 0x40135761
	global_load_dwordx4 v[128:131], v220, s[12:13] offset:0
	global_load_dwordx4 v[132:135], v220, s[18:19] offset:0
	global_load_dwordx4 v[136:139], v220, s[20:21] offset:0
	global_load_dwordx4 v[140:143], v220, s[10:11] offset:0
	global_load_dwordx4 v[144:147], v220, s[12:13] offset:64
	global_load_dwordx4 v[148:151], v220, s[18:19] offset:64
	global_load_dwordx4 v[152:155], v220, s[20:21] offset:64
	global_load_dwordx4 v[156:159], v220, s[10:11] offset:64
	v_mov_b32_e32 v225, v221
	global_load_dwordx2 v[162:163], v225, s[46:47] offset:0
	global_load_dwordx2 v[164:165], v225, s[14:15] offset:0
	global_load_dwordx2 v[166:167], v225, s[16:17] offset:0
	global_load_dwordx2 v[168:169], v225, s[46:47] offset:32
	global_load_dwordx2 v[170:171], v225, s[14:15] offset:32
	global_load_dwordx2 v[172:173], v225, s[16:17] offset:32
	v_add_u32_e32 v225, 0x2c000, v221
	global_load_dwordx2 v[174:175], v225, s[46:47] offset:0
	global_load_dwordx2 v[176:177], v225, s[14:15] offset:0
	global_load_dwordx2 v[178:179], v225, s[16:17] offset:0
	global_load_dwordx2 v[180:181], v225, s[46:47] offset:32
	global_load_dwordx2 v[182:183], v225, s[14:15] offset:32
	global_load_dwordx2 v[184:185], v225, s[16:17] offset:32
	v_add_u32_e32 v225, 0x58000, v221
	global_load_dwordx2 v[186:187], v225, s[46:47] offset:0
	global_load_dwordx2 v[188:189], v225, s[14:15] offset:0
	global_load_dwordx2 v[190:191], v225, s[16:17] offset:0
	global_load_dwordx2 v[192:193], v225, s[46:47] offset:32
	global_load_dwordx2 v[194:195], v225, s[14:15] offset:32
	global_load_dwordx2 v[196:197], v225, s[16:17] offset:32
	v_add_u32_e32 v225, 0x84000, v221
	global_load_dwordx2 v[198:199], v225, s[46:47] offset:0
	global_load_dwordx2 v[200:201], v225, s[14:15] offset:0
	global_load_dwordx2 v[202:203], v225, s[16:17] offset:0
	global_load_dwordx2 v[214:215], v225, s[46:47] offset:32
	global_load_dwordx2 v[216:217], v225, s[14:15] offset:32
	global_load_dwordx2 v[218:219], v225, s[16:17] offset:32
	s_waitcnt vmcnt(0)
	v_mov_b32_e32 v228, v224
	v_and_b32_e32 v228, s31, v228
	v_cmp_ne_u32_e32 vcc, 0, v228
	s_nop 1
	v_cndmask_b32_e64 v226, 0, -1, vcc
	v_and_b32_e32 v164, v226, v164
	v_and_b32_e32 v165, v226, v165
	v_lshlrev_b32_e32 v236, 16, v164
	v_and_b32_e32 v237, 0xffff0000, v164
	v_lshlrev_b32_e32 v238, 16, v165
	v_and_b32_e32 v239, 0xffff0000, v165
	v_lshlrev_b32_e32 v240, 16, v162
	v_and_b32_e32 v241, 0xffff0000, v162
	v_lshlrev_b32_e32 v242, 16, v163
	v_and_b32_e32 v243, 0xffff0000, v163
	v_lshlrev_b32_e32 v244, 16, v166
	v_and_b32_e32 v245, 0xffff0000, v166
	v_lshlrev_b32_e32 v246, 16, v167
	v_and_b32_e32 v247, 0xffff0000, v167
	v_pk_mul_f32 v[236:237], v[236:237], v[128:129]
	v_pk_mul_f32 v[238:239], v[238:239], v[130:131]
	v_pk_fma_f32 v[248:249], v[132:133], v[240:241], v[236:237]
	v_pk_fma_f32 v[236:237], v[134:135], v[242:243], v[238:239]
	v_pk_fma_f32 v[248:249], v[244:245], v[136:137], v[248:249]
	v_pk_fma_f32 v[236:237], v[246:247], v[138:139], v[236:237]
	v_pk_add_f32 v[248:249], v[140:141], v[248:249]
	v_pk_add_f32 v[236:237], v[142:143], v[236:237]
	v_pk_mul_f32 v[250:251], v[248:249], v[248:249]
	v_pk_mul_f32 v[252:253], v[236:237], v[236:237]
	v_pk_fma_f32 v[250:251], v[250:251], s[96:97], v[232:233] op_sel_hi:[1,0,1]
	v_pk_fma_f32 v[252:253], v[252:253], s[96:97], v[232:233] op_sel_hi:[1,0,1]
	v_pk_mul_f32 v[250:251], v[248:249], v[250:251]
	v_pk_mul_f32 v[252:253], v[236:237], v[252:253]
	v_exp_f32_e32 v250, v250
	v_exp_f32_e32 v251, v251
	v_exp_f32_e32 v252, v252
	v_exp_f32_e32 v253, v253
	v_pk_add_f32 v[250:251], v[250:251], 1.0 op_sel_hi:[1,0]
	v_pk_add_f32 v[252:253], v[252:253], 1.0 op_sel_hi:[1,0]
	v_rcp_f32_e32 v250, v250
	v_rcp_f32_e32 v251, v251
	v_rcp_f32_e32 v252, v252
	v_rcp_f32_e32 v253, v253
	v_pk_fma_f32 v[250:251], v[248:249], v[250:251], v[248:249] neg_lo:[1,0,0] neg_hi:[1,0,0]
	v_pk_fma_f32 v[252:253], v[236:237], v[252:253], v[236:237] neg_lo:[1,0,0] neg_hi:[1,0,0]
	v_pk_mul_f32 v[250:251], v[124:125], v[250:251]
	v_pk_mul_f32 v[252:253], v[126:127], v[252:253]
	v_cvt_pk_bf16_f32 v248, v250, v251
	v_cvt_pk_bf16_f32 v249, v252, v253
; #define PUT(val) *(uint2*)(g_smem + est_off(rl_, cl)) = pack4(val)
; #define STAGED2(WBODY, SBODY) { { constexpr int AIV = 0; (void)AIV; HLOOP(0, WBODY) __syncthreads(); WLOOP(0, SBODY) } __syncthreads(); { constexpr int AIV = 1; (void)AIV; HLOOP(1, WBODY) __syncthreads(); WLOOP(1, SBODY) } }
; __device__ __forceinline__ float gelu_tanh(float x) {
;   float u = 0.7978845608028654f * (x + 0.044715f * x * x * x);
;   float e = __expf(2.f * u);
;   float t = 1.f - 2.f * __builtin_amdgcn_rcpf(e + 1.f);
;   return 0.5f * x * (1.f + t);
; }
; __device__ __forceinline__ void gemm_epi(const Job& J, f32x4 (&acc)[2][2][4][2], int brow, int bcol, int wvs) {
;     ...
;     STAGED2(({ int pos = R & ((1 << lg) - 1); const u16* gp = G + (long)R * DFF + Cc;
;         f32x4 g0 = unpack4(*(const uint2*)gp), gm = {0.f, 0.f, 0.f, 0.f}, gn = {0.f, 0.f, 0.f, 0.f};
;         if (pos > 0) gm = unpack4(*(const uint2*)(gp - DFF));
;         if (pos < (1 << lg) - 1) gn = unpack4(*(const uint2*)(gp + DFF));
;         f32x4 w0 = *(const f32x4*)(cw + Cc), w1 = *(const f32x4*)(cw + DFF + Cc), w2 = *(const f32x4*)(cw + 2 * DFF + Cc), bb = *(const f32x4*)(cb + Cc);
;         f32x4 o; _Pragma("unroll") for (int j = 0; j < 4; ++j) { float cv = gm[j] * w0[j] + g0[j] * w1[j] + gn[j] * w2[j] + bb[j]; o[j] = gelu_tanh(cv) * v[j]; }
;         PUT(o); }), ({ *(u32x4*)(C + (long)R * ldc + Cc) = LDV; })) } break;
	ds_write_b64 v222, v[248:249] offset:32768
	v_and_b32_e32 v170, v226, v170
	v_and_b32_e32 v171, v226, v171
	v_lshlrev_b32_e32 v236, 16, v170
	v_and_b32_e32 v237, 0xffff0000, v170
	v_lshlrev_b32_e32 v238, 16, v171
	v_and_b32_e32 v239, 0xffff0000, v171
	v_lshlrev_b32_e32 v240, 16, v168
	v_and_b32_e32 v241, 0xffff0000, v168
	v_lshlrev_b32_e32 v242, 16, v169
	v_and_b32_e32 v243, 0xffff0000, v169
	v_lshlrev_b32_e32 v244, 16, v172
	v_and_b32_e32 v245, 0xffff0000, v172
	v_lshlrev_b32_e32 v246, 16, v173
	v_and_b32_e32 v247, 0xffff0000, v173
	v_pk_mul_f32 v[236:237], v[236:237], v[144:145]
	v_pk_mul_f32 v[238:239], v[238:239], v[146:147]
	v_pk_fma_f32 v[248:249], v[148:149], v[240:241], v[236:237]
	v_pk_fma_f32 v[236:237], v[150:151], v[242:243], v[238:239]
	v_pk_fma_f32 v[248:249], v[244:245], v[152:153], v[248:249]
	v_pk_fma_f32 v[236:237], v[246:247], v[154:155], v[236:237]
	v_pk_add_f32 v[248:249], v[156:157], v[248:249]
	v_pk_add_f32 v[236:237], v[158:159], v[236:237]
	v_pk_mul_f32 v[250:251], v[248:249], v[248:249]
	v_pk_mul_f32 v[252:253], v[236:237], v[236:237]
	v_pk_fma_f32 v[250:251], v[250:251], s[96:97], v[232:233] op_sel_hi:[1,0,1]
	v_pk_fma_f32 v[252:253], v[252:253], s[96:97], v[232:233] op_sel_hi:[1,0,1]
	v_pk_mul_f32 v[250:251], v[248:249], v[250:251]
	v_pk_mul_f32 v[252:253], v[236:237], v[252:253]
	v_exp_f32_e32 v250, v250
	v_exp_f32_e32 v251, v251
	v_exp_f32_e32 v252, v252
	v_exp_f32_e32 v253, v253
	v_pk_add_f32 v[250:251], v[250:251], 1.0 op_sel_hi:[1,0]
	v_pk_add_f32 v[252:253], v[252:253], 1.0 op_sel_hi:[1,0]
	v_rcp_f32_e32 v250, v250
	v_rcp_f32_e32 v251, v251
	v_rcp_f32_e32 v252, v252
	v_rcp_f32_e32 v253, v253
	v_pk_fma_f32 v[250:251], v[248:249], v[250:251], v[248:249] neg_lo:[1,0,0] neg_hi:[1,0,0]
	v_pk_fma_f32 v[252:253], v[236:237], v[252:253], v[236:237] neg_lo:[1,0,0] neg_hi:[1,0,0]
	v_pk_mul_f32 v[250:251], v[120:121], v[250:251]
	v_pk_mul_f32 v[252:253], v[122:123], v[252:253]
	v_cvt_pk_bf16_f32 v248, v250, v251
	v_cvt_pk_bf16_f32 v249, v252, v253
	ds_write_b64 v223, v[248:249] offset:32768
	v_lshlrev_b32_e32 v236, 16, v176
	v_and_b32_e32 v237, 0xffff0000, v176
	v_lshlrev_b32_e32 v238, 16, v177
	v_and_b32_e32 v239, 0xffff0000, v177
	v_lshlrev_b32_e32 v240, 16, v174
	v_and_b32_e32 v241, 0xffff0000, v174
	v_lshlrev_b32_e32 v242, 16, v175
	v_and_b32_e32 v243, 0xffff0000, v175
	v_lshlrev_b32_e32 v244, 16, v178
	v_and_b32_e32 v245, 0xffff0000, v178
	v_lshlrev_b32_e32 v246, 16, v179
	v_and_b32_e32 v247, 0xffff0000, v179
	v_pk_mul_f32 v[236:237], v[236:237], v[128:129]
	v_pk_mul_f32 v[238:239], v[238:239], v[130:131]
	v_pk_fma_f32 v[248:249], v[132:133], v[240:241], v[236:237]
	v_pk_fma_f32 v[236:237], v[134:135], v[242:243], v[238:239]
	v_pk_fma_f32 v[248:249], v[244:245], v[136:137], v[248:249]
	v_pk_fma_f32 v[236:237], v[246:247], v[138:139], v[236:237]
	v_pk_add_f32 v[248:249], v[140:141], v[248:249]
	v_pk_add_f32 v[236:237], v[142:143], v[236:237]
	v_pk_mul_f32 v[250:251], v[248:249], v[248:249]
	v_pk_mul_f32 v[252:253], v[236:237], v[236:237]
	v_pk_fma_f32 v[250:251], v[250:251], s[96:97], v[232:233] op_sel_hi:[1,0,1]
	v_pk_fma_f32 v[252:253], v[252:253], s[96:97], v[232:233] op_sel_hi:[1,0,1]
	v_pk_mul_f32 v[250:251], v[248:249], v[250:251]
	v_pk_mul_f32 v[252:253], v[236:237], v[252:253]
	v_exp_f32_e32 v250, v250
	v_exp_f32_e32 v251, v251
	v_exp_f32_e32 v252, v252
	v_exp_f32_e32 v253, v253
	v_pk_add_f32 v[250:251], v[250:251], 1.0 op_sel_hi:[1,0]
	v_pk_add_f32 v[252:253], v[252:253], 1.0 op_sel_hi:[1,0]
	v_rcp_f32_e32 v250, v250
	v_rcp_f32_e32 v251, v251
	v_rcp_f32_e32 v252, v252
	v_rcp_f32_e32 v253, v253
	v_pk_fma_f32 v[250:251], v[248:249], v[250:251], v[248:249] neg_lo:[1,0,0] neg_hi:[1,0,0]
	v_pk_fma_f32 v[252:253], v[236:237], v[252:253], v[236:237] neg_lo:[1,0,0] neg_hi:[1,0,0]
	v_pk_mul_f32 v[250:251], v[116:117], v[250:251]
	v_pk_mul_f32 v[252:253], v[118:119], v[252:253]
	v_cvt_pk_bf16_f32 v248, v250, v251
	v_cvt_pk_bf16_f32 v249, v252, v253
	ds_write_b64 v222, v[248:249] offset:41216
	v_lshlrev_b32_e32 v236, 16, v182
	v_and_b32_e32 v237, 0xffff0000, v182
	v_lshlrev_b32_e32 v238, 16, v183
	v_and_b32_e32 v239, 0xffff0000, v183
	v_lshlrev_b32_e32 v240, 16, v180
	v_and_b32_e32 v241, 0xffff0000, v180
	v_lshlrev_b32_e32 v242, 16, v181
	v_and_b32_e32 v243, 0xffff0000, v181
	v_lshlrev_b32_e32 v244, 16, v184
	v_and_b32_e32 v245, 0xffff0000, v184
	v_lshlrev_b32_e32 v246, 16, v185
	v_and_b32_e32 v247, 0xffff0000, v185
	v_pk_mul_f32 v[236:237], v[236:237], v[144:145]
	v_pk_mul_f32 v[238:239], v[238:239], v[146:147]
	v_pk_fma_f32 v[248:249], v[148:149], v[240:241], v[236:237]
	v_pk_fma_f32 v[236:237], v[150:151], v[242:243], v[238:239]
	v_pk_fma_f32 v[248:249], v[244:245], v[152:153], v[248:249]
	v_pk_fma_f32 v[236:237], v[246:247], v[154:155], v[236:237]
	v_pk_add_f32 v[248:249], v[156:157], v[248:249]
	v_pk_add_f32 v[236:237], v[158:159], v[236:237]
	v_pk_mul_f32 v[250:251], v[248:249], v[248:249]
	v_pk_mul_f32 v[252:253], v[236:237], v[236:237]
	v_pk_fma_f32 v[250:251], v[250:251], s[96:97], v[232:233] op_sel_hi:[1,0,1]
	v_pk_fma_f32 v[252:253], v[252:253], s[96:97], v[232:233] op_sel_hi:[1,0,1]
	v_pk_mul_f32 v[250:251], v[248:249], v[250:251]
	v_pk_mul_f32 v[252:253], v[236:237], v[252:253]
	v_exp_f32_e32 v250, v250
	v_exp_f32_e32 v251, v251
	v_exp_f32_e32 v252, v252
	v_exp_f32_e32 v253, v253
	v_pk_add_f32 v[250:251], v[250:251], 1.0 op_sel_hi:[1,0]
	v_pk_add_f32 v[252:253], v[252:253], 1.0 op_sel_hi:[1,0]
	v_rcp_f32_e32 v250, v250
	v_rcp_f32_e32 v251, v251
	v_rcp_f32_e32 v252, v252
	v_rcp_f32_e32 v253, v253
	v_pk_fma_f32 v[250:251], v[248:249], v[250:251], v[248:249] neg_lo:[1,0,0] neg_hi:[1,0,0]
; #define PUT(val) *(uint2*)(g_smem + est_off(rl_, cl)) = pack4(val)
; #define STAGED2(WBODY, SBODY) { { constexpr int AIV = 0; (void)AIV; HLOOP(0, WBODY) __syncthreads(); WLOOP(0, SBODY) } __syncthreads(); { constexpr int AIV = 1; (void)AIV; HLOOP(1, WBODY) __syncthreads(); WLOOP(1, SBODY) } }
; __device__ __forceinline__ float gelu_tanh(float x) {
;   float u = 0.7978845608028654f * (x + 0.044715f * x * x * x);
;   float e = __expf(2.f * u);
;   float t = 1.f - 2.f * __builtin_amdgcn_rcpf(e + 1.f);
;   return 0.5f * x * (1.f + t);
; }
; __device__ __forceinline__ void gemm_epi(const Job& J, f32x4 (&acc)[2][2][4][2], int brow, int bcol, int wvs) {
;     ...
;     STAGED2(({ int pos = R & ((1 << lg) - 1); const u16* gp = G + (long)R * DFF + Cc;
;         f32x4 g0 = unpack4(*(const uint2*)gp), gm = {0.f, 0.f, 0.f, 0.f}, gn = {0.f, 0.f, 0.f, 0.f};
;         if (pos > 0) gm = unpack4(*(const uint2*)(gp - DFF));
;         if (pos < (1 << lg) - 1) gn = unpack4(*(const uint2*)(gp + DFF));
;         f32x4 w0 = *(const f32x4*)(cw + Cc), w1 = *(const f32x4*)(cw + DFF + Cc), w2 = *(const f32x4*)(cw + 2 * DFF + Cc), bb = *(const f32x4*)(cb + Cc);
;         f32x4 o; _Pragma("unroll") for (int j = 0; j < 4; ++j) { float cv = gm[j] * w0[j] + g0[j] * w1[j] + gn[j] * w2[j] + bb[j]; o[j] = gelu_tanh(cv) * v[j]; }
;         PUT(o); }), ({ *(u32x4*)(C + (long)R * ldc + Cc) = LDV; })) } break;
	v_pk_fma_f32 v[252:253], v[236:237], v[252:253], v[236:237] neg_lo:[1,0,0] neg_hi:[1,0,0]
	v_pk_mul_f32 v[250:251], v[112:113], v[250:251]
	v_pk_mul_f32 v[252:253], v[114:115], v[252:253]
	v_cvt_pk_bf16_f32 v248, v250, v251
	v_cvt_pk_bf16_f32 v249, v252, v253
	ds_write_b64 v223, v[248:249] offset:41216
	v_lshlrev_b32_e32 v236, 16, v188
	v_and_b32_e32 v237, 0xffff0000, v188
	v_lshlrev_b32_e32 v238, 16, v189
	v_and_b32_e32 v239, 0xffff0000, v189
	v_lshlrev_b32_e32 v240, 16, v186
	v_and_b32_e32 v241, 0xffff0000, v186
	v_lshlrev_b32_e32 v242, 16, v187
	v_and_b32_e32 v243, 0xffff0000, v187
	v_lshlrev_b32_e32 v244, 16, v190
	v_and_b32_e32 v245, 0xffff0000, v190
	v_lshlrev_b32_e32 v246, 16, v191
	v_and_b32_e32 v247, 0xffff0000, v191
	v_pk_mul_f32 v[236:237], v[236:237], v[128:129]
	v_pk_mul_f32 v[238:239], v[238:239], v[130:131]
	v_pk_fma_f32 v[248:249], v[132:133], v[240:241], v[236:237]
	v_pk_fma_f32 v[236:237], v[134:135], v[242:243], v[238:239]
	v_pk_fma_f32 v[248:249], v[244:245], v[136:137], v[248:249]
	v_pk_fma_f32 v[236:237], v[246:247], v[138:139], v[236:237]
	v_pk_add_f32 v[248:249], v[140:141], v[248:249]
	v_pk_add_f32 v[236:237], v[142:143], v[236:237]
	v_pk_mul_f32 v[250:251], v[248:249], v[248:249]
	v_pk_mul_f32 v[252:253], v[236:237], v[236:237]
	v_pk_fma_f32 v[250:251], v[250:251], s[96:97], v[232:233] op_sel_hi:[1,0,1]
	v_pk_fma_f32 v[252:253], v[252:253], s[96:97], v[232:233] op_sel_hi:[1,0,1]
	v_pk_mul_f32 v[250:251], v[248:249], v[250:251]
	v_pk_mul_f32 v[252:253], v[236:237], v[252:253]
	v_exp_f32_e32 v250, v250
	v_exp_f32_e32 v251, v251
	v_exp_f32_e32 v252, v252
	v_exp_f32_e32 v253, v253
	v_pk_add_f32 v[250:251], v[250:251], 1.0 op_sel_hi:[1,0]
	v_pk_add_f32 v[252:253], v[252:253], 1.0 op_sel_hi:[1,0]
	v_rcp_f32_e32 v250, v250
	v_rcp_f32_e32 v251, v251
	v_rcp_f32_e32 v252, v252
	v_rcp_f32_e32 v253, v253
	v_pk_fma_f32 v[250:251], v[248:249], v[250:251], v[248:249] neg_lo:[1,0,0] neg_hi:[1,0,0]
	v_pk_fma_f32 v[252:253], v[236:237], v[252:253], v[236:237] neg_lo:[1,0,0] neg_hi:[1,0,0]
	v_pk_mul_f32 v[250:251], v[108:109], v[250:251]
	v_pk_mul_f32 v[252:253], v[110:111], v[252:253]
	v_cvt_pk_bf16_f32 v248, v250, v251
	v_cvt_pk_bf16_f32 v249, v252, v253
	ds_write_b64 v222, v[248:249] offset:49152
	v_lshlrev_b32_e32 v236, 16, v194
	v_and_b32_e32 v237, 0xffff0000, v194
	v_lshlrev_b32_e32 v238, 16, v195
	v_and_b32_e32 v239, 0xffff0000, v195
	v_lshlrev_b32_e32 v240, 16, v192
	v_and_b32_e32 v241, 0xffff0000, v192
	v_lshlrev_b32_e32 v242, 16, v193
	v_and_b32_e32 v243, 0xffff0000, v193
	v_lshlrev_b32_e32 v244, 16, v196
	v_and_b32_e32 v245, 0xffff0000, v196
	v_lshlrev_b32_e32 v246, 16, v197
	v_and_b32_e32 v247, 0xffff0000, v197
	v_pk_mul_f32 v[236:237], v[236:237], v[144:145]
	v_pk_mul_f32 v[238:239], v[238:239], v[146:147]
	v_pk_fma_f32 v[248:249], v[148:149], v[240:241], v[236:237]
	v_pk_fma_f32 v[236:237], v[150:151], v[242:243], v[238:239]
	v_pk_fma_f32 v[248:249], v[244:245], v[152:153], v[248:249]
	v_pk_fma_f32 v[236:237], v[246:247], v[154:155], v[236:237]
	v_pk_add_f32 v[248:249], v[156:157], v[248:249]
	v_pk_add_f32 v[236:237], v[158:159], v[236:237]
	v_pk_mul_f32 v[250:251], v[248:249], v[248:249]
	v_pk_mul_f32 v[252:253], v[236:237], v[236:237]
	v_pk_fma_f32 v[250:251], v[250:251], s[96:97], v[232:233] op_sel_hi:[1,0,1]
	v_pk_fma_f32 v[252:253], v[252:253], s[96:97], v[232:233] op_sel_hi:[1,0,1]
	v_pk_mul_f32 v[250:251], v[248:249], v[250:251]
	v_pk_mul_f32 v[252:253], v[236:237], v[252:253]
	v_exp_f32_e32 v250, v250
	v_exp_f32_e32 v251, v251
	v_exp_f32_e32 v252, v252
	v_exp_f32_e32 v253, v253
	v_pk_add_f32 v[250:251], v[250:251], 1.0 op_sel_hi:[1,0]
	v_pk_add_f32 v[252:253], v[252:253], 1.0 op_sel_hi:[1,0]
	v_rcp_f32_e32 v250, v250
	v_rcp_f32_e32 v251, v251
	v_rcp_f32_e32 v252, v252
	v_rcp_f32_e32 v253, v253
	v_pk_fma_f32 v[250:251], v[248:249], v[250:251], v[248:249] neg_lo:[1,0,0] neg_hi:[1,0,0]
	v_pk_fma_f32 v[252:253], v[236:237], v[252:253], v[236:237] neg_lo:[1,0,0] neg_hi:[1,0,0]
	v_pk_mul_f32 v[250:251], v[104:105], v[250:251]
	v_pk_mul_f32 v[252:253], v[106:107], v[252:253]
	v_cvt_pk_bf16_f32 v248, v250, v251
	v_cvt_pk_bf16_f32 v249, v252, v253
	ds_write_b64 v223, v[248:249] offset:49152
	v_lshlrev_b32_e32 v236, 16, v200
	v_and_b32_e32 v237, 0xffff0000, v200
	v_lshlrev_b32_e32 v238, 16, v201
	v_and_b32_e32 v239, 0xffff0000, v201
	v_lshlrev_b32_e32 v240, 16, v198
	v_and_b32_e32 v241, 0xffff0000, v198
	v_lshlrev_b32_e32 v242, 16, v199
	v_and_b32_e32 v243, 0xffff0000, v199
	v_lshlrev_b32_e32 v244, 16, v202
	v_and_b32_e32 v245, 0xffff0000, v202
	v_lshlrev_b32_e32 v246, 16, v203
	v_and_b32_e32 v247, 0xffff0000, v203
	v_pk_mul_f32 v[236:237], v[236:237], v[128:129]
	v_pk_mul_f32 v[238:239], v[238:239], v[130:131]
	v_pk_fma_f32 v[248:249], v[132:133], v[240:241], v[236:237]
	v_pk_fma_f32 v[236:237], v[134:135], v[242:243], v[238:239]
	v_pk_fma_f32 v[248:249], v[244:245], v[136:137], v[248:249]
	v_pk_fma_f32 v[236:237], v[246:247], v[138:139], v[236:237]
	v_pk_add_f32 v[248:249], v[140:141], v[248:249]
	v_pk_add_f32 v[236:237], v[142:143], v[236:237]
	v_pk_mul_f32 v[250:251], v[248:249], v[248:249]
	v_pk_mul_f32 v[252:253], v[236:237], v[236:237]
	v_pk_fma_f32 v[250:251], v[250:251], s[96:97], v[232:233] op_sel_hi:[1,0,1]
	v_pk_fma_f32 v[252:253], v[252:253], s[96:97], v[232:233] op_sel_hi:[1,0,1]
	v_pk_mul_f32 v[250:251], v[248:249], v[250:251]
	v_pk_mul_f32 v[252:253], v[236:237], v[252:253]
	v_exp_f32_e32 v250, v250
	v_exp_f32_e32 v251, v251
	v_exp_f32_e32 v252, v252
	v_exp_f32_e32 v253, v253
	v_pk_add_f32 v[250:251], v[250:251], 1.0 op_sel_hi:[1,0]
	v_pk_add_f32 v[252:253], v[252:253], 1.0 op_sel_hi:[1,0]
; #define PUT(val) *(uint2*)(g_smem + est_off(rl_, cl)) = pack4(val)
; #define STAGED2(WBODY, SBODY) { { constexpr int AIV = 0; (void)AIV; HLOOP(0, WBODY) __syncthreads(); WLOOP(0, SBODY) } __syncthreads(); { constexpr int AIV = 1; (void)AIV; HLOOP(1, WBODY) __syncthreads(); WLOOP(1, SBODY) } }
; __device__ __forceinline__ float gelu_tanh(float x) {
;   float u = 0.7978845608028654f * (x + 0.044715f * x * x * x);
;   float e = __expf(2.f * u);
;   float t = 1.f - 2.f * __builtin_amdgcn_rcpf(e + 1.f);
;   return 0.5f * x * (1.f + t);
; }
; __device__ __forceinline__ void gemm_epi(const Job& J, f32x4 (&acc)[2][2][4][2], int brow, int bcol, int wvs) {
;     ...
;     STAGED2(({ int pos = R & ((1 << lg) - 1); const u16* gp = G + (long)R * DFF + Cc;
;         f32x4 g0 = unpack4(*(const uint2*)gp), gm = {0.f, 0.f, 0.f, 0.f}, gn = {0.f, 0.f, 0.f, 0.f};
;         if (pos > 0) gm = unpack4(*(const uint2*)(gp - DFF));
;         if (pos < (1 << lg) - 1) gn = unpack4(*(const uint2*)(gp + DFF));
;         f32x4 w0 = *(const f32x4*)(cw + Cc), w1 = *(const f32x4*)(cw + DFF + Cc), w2 = *(const f32x4*)(cw + 2 * DFF + Cc), bb = *(const f32x4*)(cb + Cc);
;         f32x4 o; _Pragma("unroll") for (int j = 0; j < 4; ++j) { float cv = gm[j] * w0[j] + g0[j] * w1[j] + gn[j] * w2[j] + bb[j]; o[j] = gelu_tanh(cv) * v[j]; }
;         PUT(o); }), ({ *(u32x4*)(C + (long)R * ldc + Cc) = LDV; })) } break;
	v_rcp_f32_e32 v250, v250
	v_rcp_f32_e32 v251, v251
	v_rcp_f32_e32 v252, v252
	v_rcp_f32_e32 v253, v253
	v_pk_fma_f32 v[250:251], v[248:249], v[250:251], v[248:249] neg_lo:[1,0,0] neg_hi:[1,0,0]
	v_pk_fma_f32 v[252:253], v[236:237], v[252:253], v[236:237] neg_lo:[1,0,0] neg_hi:[1,0,0]
	v_pk_mul_f32 v[250:251], v[100:101], v[250:251]
	v_pk_mul_f32 v[252:253], v[102:103], v[252:253]
	v_cvt_pk_bf16_f32 v248, v250, v251
	v_cvt_pk_bf16_f32 v249, v252, v253
	ds_write_b64 v222, v[248:249] offset:57600
	v_lshlrev_b32_e32 v236, 16, v216
	v_and_b32_e32 v237, 0xffff0000, v216
	v_lshlrev_b32_e32 v238, 16, v217
	v_and_b32_e32 v239, 0xffff0000, v217
	v_lshlrev_b32_e32 v240, 16, v214
	v_and_b32_e32 v241, 0xffff0000, v214
	v_lshlrev_b32_e32 v242, 16, v215
	v_and_b32_e32 v243, 0xffff0000, v215
	v_lshlrev_b32_e32 v244, 16, v218
	v_and_b32_e32 v245, 0xffff0000, v218
	v_lshlrev_b32_e32 v246, 16, v219
	v_and_b32_e32 v247, 0xffff0000, v219
	v_pk_mul_f32 v[236:237], v[236:237], v[144:145]
	v_pk_mul_f32 v[238:239], v[238:239], v[146:147]
	v_pk_fma_f32 v[248:249], v[148:149], v[240:241], v[236:237]
	v_pk_fma_f32 v[236:237], v[150:151], v[242:243], v[238:239]
	v_pk_fma_f32 v[248:249], v[244:245], v[152:153], v[248:249]
	v_pk_fma_f32 v[236:237], v[246:247], v[154:155], v[236:237]
	v_pk_add_f32 v[248:249], v[156:157], v[248:249]
	v_pk_add_f32 v[236:237], v[158:159], v[236:237]
	v_pk_mul_f32 v[250:251], v[248:249], v[248:249]
	v_pk_mul_f32 v[252:253], v[236:237], v[236:237]
	v_pk_fma_f32 v[250:251], v[250:251], s[96:97], v[232:233] op_sel_hi:[1,0,1]
	v_pk_fma_f32 v[252:253], v[252:253], s[96:97], v[232:233] op_sel_hi:[1,0,1]
	v_pk_mul_f32 v[250:251], v[248:249], v[250:251]
	v_pk_mul_f32 v[252:253], v[236:237], v[252:253]
	v_exp_f32_e32 v250, v250
	v_exp_f32_e32 v251, v251
	v_exp_f32_e32 v252, v252
	v_exp_f32_e32 v253, v253
	v_pk_add_f32 v[250:251], v[250:251], 1.0 op_sel_hi:[1,0]
	v_pk_add_f32 v[252:253], v[252:253], 1.0 op_sel_hi:[1,0]
	v_rcp_f32_e32 v250, v250
	v_rcp_f32_e32 v251, v251
	v_rcp_f32_e32 v252, v252
	v_rcp_f32_e32 v253, v253
	v_pk_fma_f32 v[250:251], v[248:249], v[250:251], v[248:249] neg_lo:[1,0,0] neg_hi:[1,0,0]
	v_pk_fma_f32 v[252:253], v[236:237], v[252:253], v[236:237] neg_lo:[1,0,0] neg_hi:[1,0,0]
	v_pk_mul_f32 v[250:251], v[92:93], v[250:251]
	v_pk_mul_f32 v[252:253], v[94:95], v[252:253]
	v_cvt_pk_bf16_f32 v248, v250, v251
	v_cvt_pk_bf16_f32 v249, v252, v253
	ds_write_b64 v223, v[248:249] offset:57600
	global_load_dwordx4 v[128:131], v220, s[12:13] offset:512
	global_load_dwordx4 v[132:135], v220, s[18:19] offset:512
	global_load_dwordx4 v[136:139], v220, s[20:21] offset:512
	global_load_dwordx4 v[140:143], v220, s[10:11] offset:512
	global_load_dwordx4 v[144:147], v220, s[12:13] offset:576
	global_load_dwordx4 v[148:151], v220, s[18:19] offset:576
	global_load_dwordx4 v[152:155], v220, s[20:21] offset:576
	global_load_dwordx4 v[156:159], v220, s[10:11] offset:576
	v_mov_b32_e32 v225, v221
	global_load_dwordx2 v[162:163], v225, s[46:47] offset:256
	global_load_dwordx2 v[164:165], v225, s[14:15] offset:256
	global_load_dwordx2 v[166:167], v225, s[16:17] offset:256
	global_load_dwordx2 v[168:169], v225, s[46:47] offset:288
	global_load_dwordx2 v[170:171], v225, s[14:15] offset:288
	global_load_dwordx2 v[172:173], v225, s[16:17] offset:288
	v_add_u32_e32 v225, 0x2c000, v221
	global_load_dwordx2 v[174:175], v225, s[46:47] offset:256
	global_load_dwordx2 v[176:177], v225, s[14:15] offset:256
	global_load_dwordx2 v[178:179], v225, s[16:17] offset:256
	global_load_dwordx2 v[180:181], v225, s[46:47] offset:288
	global_load_dwordx2 v[182:183], v225, s[14:15] offset:288
	global_load_dwordx2 v[184:185], v225, s[16:17] offset:288
	v_add_u32_e32 v225, 0x58000, v221
	global_load_dwordx2 v[186:187], v225, s[46:47] offset:256
	global_load_dwordx2 v[188:189], v225, s[14:15] offset:256
	global_load_dwordx2 v[190:191], v225, s[16:17] offset:256
	global_load_dwordx2 v[192:193], v225, s[46:47] offset:288
	global_load_dwordx2 v[194:195], v225, s[14:15] offset:288
	global_load_dwordx2 v[196:197], v225, s[16:17] offset:288
	v_add_u32_e32 v225, 0x84000, v221
	global_load_dwordx2 v[198:199], v225, s[46:47] offset:256
	global_load_dwordx2 v[200:201], v225, s[14:15] offset:256
	global_load_dwordx2 v[202:203], v225, s[16:17] offset:256
	global_load_dwordx2 v[214:215], v225, s[46:47] offset:288
	global_load_dwordx2 v[216:217], v225, s[14:15] offset:288
	global_load_dwordx2 v[218:219], v225, s[16:17] offset:288
	s_waitcnt vmcnt(0)
; #define PUT(val) *(uint2*)(g_smem + est_off(rl_, cl)) = pack4(val)
; #define STAGED2(WBODY, SBODY) { { constexpr int AIV = 0; (void)AIV; HLOOP(0, WBODY) __syncthreads(); WLOOP(0, SBODY) } __syncthreads(); { constexpr int AIV = 1; (void)AIV; HLOOP(1, WBODY) __syncthreads(); WLOOP(1, SBODY) } }
; __device__ __forceinline__ float gelu_tanh(float x) {
;   float u = 0.7978845608028654f * (x + 0.044715f * x * x * x);
;   float e = __expf(2.f * u);
;   float t = 1.f - 2.f * __builtin_amdgcn_rcpf(e + 1.f);
;   return 0.5f * x * (1.f + t);
; }
; __device__ __forceinline__ void gemm_epi(const Job& J, f32x4 (&acc)[2][2][4][2], int brow, int bcol, int wvs) {
;     ...
;     STAGED2(({ int pos = R & ((1 << lg) - 1); const u16* gp = G + (long)R * DFF + Cc;
;         f32x4 g0 = unpack4(*(const uint2*)gp), gm = {0.f, 0.f, 0.f, 0.f}, gn = {0.f, 0.f, 0.f, 0.f};
;         if (pos > 0) gm = unpack4(*(const uint2*)(gp - DFF));
;         if (pos < (1 << lg) - 1) gn = unpack4(*(const uint2*)(gp + DFF));
;         f32x4 w0 = *(const f32x4*)(cw + Cc), w1 = *(const f32x4*)(cw + DFF + Cc), w2 = *(const f32x4*)(cw + 2 * DFF + Cc), bb = *(const f32x4*)(cb + Cc);
;         f32x4 o; _Pragma("unroll") for (int j = 0; j < 4; ++j) { float cv = gm[j] * w0[j] + g0[j] * w1[j] + gn[j] * w2[j] + bb[j]; o[j] = gelu_tanh(cv) * v[j]; }
;         PUT(o); }), ({ *(u32x4*)(C + (long)R * ldc + Cc) = LDV; })) } break;
	v_mov_b32_e32 v228, v224
	v_and_b32_e32 v228, s31, v228
	v_cmp_ne_u32_e32 vcc, 0, v228
	s_nop 1
	v_cndmask_b32_e64 v226, 0, -1, vcc
	v_and_b32_e32 v164, v226, v164
	v_and_b32_e32 v165, v226, v165
	v_lshlrev_b32_e32 v236, 16, v164
	v_and_b32_e32 v237, 0xffff0000, v164
	v_lshlrev_b32_e32 v238, 16, v165
	v_and_b32_e32 v239, 0xffff0000, v165
	v_lshlrev_b32_e32 v240, 16, v162
	v_and_b32_e32 v241, 0xffff0000, v162
	v_lshlrev_b32_e32 v242, 16, v163
	v_and_b32_e32 v243, 0xffff0000, v163
	v_lshlrev_b32_e32 v244, 16, v166
	v_and_b32_e32 v245, 0xffff0000, v166
	v_lshlrev_b32_e32 v246, 16, v167
	v_and_b32_e32 v247, 0xffff0000, v167
	v_pk_mul_f32 v[236:237], v[236:237], v[128:129]
	v_pk_mul_f32 v[238:239], v[238:239], v[130:131]
	v_pk_fma_f32 v[248:249], v[132:133], v[240:241], v[236:237]
	v_pk_fma_f32 v[236:237], v[134:135], v[242:243], v[238:239]
	v_pk_fma_f32 v[248:249], v[244:245], v[136:137], v[248:249]
	v_pk_fma_f32 v[236:237], v[246:247], v[138:139], v[236:237]
	v_pk_add_f32 v[248:249], v[140:141], v[248:249]
	v_pk_add_f32 v[236:237], v[142:143], v[236:237]
	v_pk_mul_f32 v[250:251], v[248:249], v[248:249]
	v_pk_mul_f32 v[252:253], v[236:237], v[236:237]
	v_pk_fma_f32 v[250:251], v[250:251], s[96:97], v[232:233] op_sel_hi:[1,0,1]
	v_pk_fma_f32 v[252:253], v[252:253], s[96:97], v[232:233] op_sel_hi:[1,0,1]
	v_pk_mul_f32 v[250:251], v[248:249], v[250:251]
	v_pk_mul_f32 v[252:253], v[236:237], v[252:253]
	v_exp_f32_e32 v250, v250
	v_exp_f32_e32 v251, v251
	v_exp_f32_e32 v252, v252
	v_exp_f32_e32 v253, v253
	v_pk_add_f32 v[250:251], v[250:251], 1.0 op_sel_hi:[1,0]
	v_pk_add_f32 v[252:253], v[252:253], 1.0 op_sel_hi:[1,0]
	v_rcp_f32_e32 v250, v250
	v_rcp_f32_e32 v251, v251
	v_rcp_f32_e32 v252, v252
	v_rcp_f32_e32 v253, v253
	v_pk_fma_f32 v[250:251], v[248:249], v[250:251], v[248:249] neg_lo:[1,0,0] neg_hi:[1,0,0]
	v_pk_fma_f32 v[252:253], v[236:237], v[252:253], v[236:237] neg_lo:[1,0,0] neg_hi:[1,0,0]
	v_pk_mul_f32 v[250:251], v[96:97], v[250:251]
	v_pk_mul_f32 v[252:253], v[98:99], v[252:253]
	v_cvt_pk_bf16_f32 v248, v250, v251
	v_cvt_pk_bf16_f32 v249, v252, v253
	ds_write_b64 v222, v[248:249] offset:33024
	v_and_b32_e32 v170, v226, v170
	v_and_b32_e32 v171, v226, v171
	v_lshlrev_b32_e32 v236, 16, v170
	v_and_b32_e32 v237, 0xffff0000, v170
	v_lshlrev_b32_e32 v238, 16, v171
	v_and_b32_e32 v239, 0xffff0000, v171
	v_lshlrev_b32_e32 v240, 16, v168
	v_and_b32_e32 v241, 0xffff0000, v168
	v_lshlrev_b32_e32 v242, 16, v169
	v_and_b32_e32 v243, 0xffff0000, v169
	v_lshlrev_b32_e32 v244, 16, v172
	v_and_b32_e32 v245, 0xffff0000, v172
	v_lshlrev_b32_e32 v246, 16, v173
	v_and_b32_e32 v247, 0xffff0000, v173
	v_pk_mul_f32 v[236:237], v[236:237], v[144:145]
	v_pk_mul_f32 v[238:239], v[238:239], v[146:147]
	v_pk_fma_f32 v[248:249], v[148:149], v[240:241], v[236:237]
	v_pk_fma_f32 v[236:237], v[150:151], v[242:243], v[238:239]
	v_pk_fma_f32 v[248:249], v[244:245], v[152:153], v[248:249]
	v_pk_fma_f32 v[236:237], v[246:247], v[154:155], v[236:237]
	v_pk_add_f32 v[248:249], v[156:157], v[248:249]
	v_pk_add_f32 v[236:237], v[158:159], v[236:237]
	v_pk_mul_f32 v[250:251], v[248:249], v[248:249]
	v_pk_mul_f32 v[252:253], v[236:237], v[236:237]
	v_pk_fma_f32 v[250:251], v[250:251], s[96:97], v[232:233] op_sel_hi:[1,0,1]
	v_pk_fma_f32 v[252:253], v[252:253], s[96:97], v[232:233] op_sel_hi:[1,0,1]
	v_pk_mul_f32 v[250:251], v[248:249], v[250:251]
	v_pk_mul_f32 v[252:253], v[236:237], v[252:253]
	v_exp_f32_e32 v250, v250
	v_exp_f32_e32 v251, v251
	v_exp_f32_e32 v252, v252
	v_exp_f32_e32 v253, v253
	v_pk_add_f32 v[250:251], v[250:251], 1.0 op_sel_hi:[1,0]
	v_pk_add_f32 v[252:253], v[252:253], 1.0 op_sel_hi:[1,0]
	v_rcp_f32_e32 v250, v250
	v_rcp_f32_e32 v251, v251
	v_rcp_f32_e32 v252, v252
	v_rcp_f32_e32 v253, v253
	v_pk_fma_f32 v[250:251], v[248:249], v[250:251], v[248:249] neg_lo:[1,0,0] neg_hi:[1,0,0]
	v_pk_fma_f32 v[252:253], v[236:237], v[252:253], v[236:237] neg_lo:[1,0,0] neg_hi:[1,0,0]
	v_pk_mul_f32 v[250:251], v[88:89], v[250:251]
	v_pk_mul_f32 v[252:253], v[90:91], v[252:253]
	v_cvt_pk_bf16_f32 v248, v250, v251
	v_cvt_pk_bf16_f32 v249, v252, v253
	ds_write_b64 v223, v[248:249] offset:33024
	v_lshlrev_b32_e32 v236, 16, v176
	v_and_b32_e32 v237, 0xffff0000, v176
	v_lshlrev_b32_e32 v238, 16, v177
	v_and_b32_e32 v239, 0xffff0000, v177
	v_lshlrev_b32_e32 v240, 16, v174
	v_and_b32_e32 v241, 0xffff0000, v174
	v_lshlrev_b32_e32 v242, 16, v175
	v_and_b32_e32 v243, 0xffff0000, v175
	v_lshlrev_b32_e32 v244, 16, v178
	v_and_b32_e32 v245, 0xffff0000, v178
	v_lshlrev_b32_e32 v246, 16, v179
	v_and_b32_e32 v247, 0xffff0000, v179
	v_pk_mul_f32 v[236:237], v[236:237], v[128:129]
	v_pk_mul_f32 v[238:239], v[238:239], v[130:131]
	v_pk_fma_f32 v[248:249], v[132:133], v[240:241], v[236:237]
	v_pk_fma_f32 v[236:237], v[134:135], v[242:243], v[238:239]
	v_pk_fma_f32 v[248:249], v[244:245], v[136:137], v[248:249]
	v_pk_fma_f32 v[236:237], v[246:247], v[138:139], v[236:237]
	v_pk_add_f32 v[248:249], v[140:141], v[248:249]
	v_pk_add_f32 v[236:237], v[142:143], v[236:237]
	v_pk_mul_f32 v[250:251], v[248:249], v[248:249]
	v_pk_mul_f32 v[252:253], v[236:237], v[236:237]
	v_pk_fma_f32 v[250:251], v[250:251], s[96:97], v[232:233] op_sel_hi:[1,0,1]
	v_pk_fma_f32 v[252:253], v[252:253], s[96:97], v[232:233] op_sel_hi:[1,0,1]
	v_pk_mul_f32 v[250:251], v[248:249], v[250:251]
	v_pk_mul_f32 v[252:253], v[236:237], v[252:253]
	v_exp_f32_e32 v250, v250
	v_exp_f32_e32 v251, v251
	v_exp_f32_e32 v252, v252
	v_exp_f32_e32 v253, v253
	v_pk_add_f32 v[250:251], v[250:251], 1.0 op_sel_hi:[1,0]
	v_pk_add_f32 v[252:253], v[252:253], 1.0 op_sel_hi:[1,0]
	v_rcp_f32_e32 v250, v250
	v_rcp_f32_e32 v251, v251
; #define PUT(val) *(uint2*)(g_smem + est_off(rl_, cl)) = pack4(val)
; #define STAGED2(WBODY, SBODY) { { constexpr int AIV = 0; (void)AIV; HLOOP(0, WBODY) __syncthreads(); WLOOP(0, SBODY) } __syncthreads(); { constexpr int AIV = 1; (void)AIV; HLOOP(1, WBODY) __syncthreads(); WLOOP(1, SBODY) } }
; __device__ __forceinline__ float gelu_tanh(float x) {
;   float u = 0.7978845608028654f * (x + 0.044715f * x * x * x);
;   float e = __expf(2.f * u);
;   float t = 1.f - 2.f * __builtin_amdgcn_rcpf(e + 1.f);
;   return 0.5f * x * (1.f + t);
; }
; __device__ __forceinline__ void gemm_epi(const Job& J, f32x4 (&acc)[2][2][4][2], int brow, int bcol, int wvs) {
;     ...
;     STAGED2(({ int pos = R & ((1 << lg) - 1); const u16* gp = G + (long)R * DFF + Cc;
;         f32x4 g0 = unpack4(*(const uint2*)gp), gm = {0.f, 0.f, 0.f, 0.f}, gn = {0.f, 0.f, 0.f, 0.f};
;         if (pos > 0) gm = unpack4(*(const uint2*)(gp - DFF));
;         if (pos < (1 << lg) - 1) gn = unpack4(*(const uint2*)(gp + DFF));
;         f32x4 w0 = *(const f32x4*)(cw + Cc), w1 = *(const f32x4*)(cw + DFF + Cc), w2 = *(const f32x4*)(cw + 2 * DFF + Cc), bb = *(const f32x4*)(cb + Cc);
;         f32x4 o; _Pragma("unroll") for (int j = 0; j < 4; ++j) { float cv = gm[j] * w0[j] + g0[j] * w1[j] + gn[j] * w2[j] + bb[j]; o[j] = gelu_tanh(cv) * v[j]; }
;         PUT(o); }), ({ *(u32x4*)(C + (long)R * ldc + Cc) = LDV; })) } break;
	v_rcp_f32_e32 v252, v252
	v_rcp_f32_e32 v253, v253
	v_pk_fma_f32 v[250:251], v[248:249], v[250:251], v[248:249] neg_lo:[1,0,0] neg_hi:[1,0,0]
	v_pk_fma_f32 v[252:253], v[236:237], v[252:253], v[236:237] neg_lo:[1,0,0] neg_hi:[1,0,0]
	v_pk_mul_f32 v[250:251], v[84:85], v[250:251]
	v_pk_mul_f32 v[252:253], v[86:87], v[252:253]
	v_cvt_pk_bf16_f32 v248, v250, v251
	v_cvt_pk_bf16_f32 v249, v252, v253
	ds_write_b64 v222, v[248:249] offset:40960
	v_lshlrev_b32_e32 v236, 16, v182
	v_and_b32_e32 v237, 0xffff0000, v182
	v_lshlrev_b32_e32 v238, 16, v183
	v_and_b32_e32 v239, 0xffff0000, v183
	v_lshlrev_b32_e32 v240, 16, v180
	v_and_b32_e32 v241, 0xffff0000, v180
	v_lshlrev_b32_e32 v242, 16, v181
	v_and_b32_e32 v243, 0xffff0000, v181
	v_lshlrev_b32_e32 v244, 16, v184
	v_and_b32_e32 v245, 0xffff0000, v184
	v_lshlrev_b32_e32 v246, 16, v185
	v_and_b32_e32 v247, 0xffff0000, v185
	v_pk_mul_f32 v[236:237], v[236:237], v[144:145]
	v_pk_mul_f32 v[238:239], v[238:239], v[146:147]
	v_pk_fma_f32 v[248:249], v[148:149], v[240:241], v[236:237]
	v_pk_fma_f32 v[236:237], v[150:151], v[242:243], v[238:239]
	v_pk_fma_f32 v[248:249], v[244:245], v[152:153], v[248:249]
	v_pk_fma_f32 v[236:237], v[246:247], v[154:155], v[236:237]
	v_pk_add_f32 v[248:249], v[156:157], v[248:249]
	v_pk_add_f32 v[236:237], v[158:159], v[236:237]
	v_pk_mul_f32 v[250:251], v[248:249], v[248:249]
	v_pk_mul_f32 v[252:253], v[236:237], v[236:237]
	v_pk_fma_f32 v[250:251], v[250:251], s[96:97], v[232:233] op_sel_hi:[1,0,1]
	v_pk_fma_f32 v[252:253], v[252:253], s[96:97], v[232:233] op_sel_hi:[1,0,1]
	v_pk_mul_f32 v[250:251], v[248:249], v[250:251]
	v_pk_mul_f32 v[252:253], v[236:237], v[252:253]
	v_exp_f32_e32 v250, v250
	v_exp_f32_e32 v251, v251
	v_exp_f32_e32 v252, v252
	v_exp_f32_e32 v253, v253
	v_pk_add_f32 v[250:251], v[250:251], 1.0 op_sel_hi:[1,0]
	v_pk_add_f32 v[252:253], v[252:253], 1.0 op_sel_hi:[1,0]
	v_rcp_f32_e32 v250, v250
	v_rcp_f32_e32 v251, v251
	v_rcp_f32_e32 v252, v252
	v_rcp_f32_e32 v253, v253
	v_pk_fma_f32 v[250:251], v[248:249], v[250:251], v[248:249] neg_lo:[1,0,0] neg_hi:[1,0,0]
	v_pk_fma_f32 v[252:253], v[236:237], v[252:253], v[236:237] neg_lo:[1,0,0] neg_hi:[1,0,0]
	v_pk_mul_f32 v[250:251], v[80:81], v[250:251]
	v_pk_mul_f32 v[252:253], v[82:83], v[252:253]
	v_cvt_pk_bf16_f32 v248, v250, v251
	v_cvt_pk_bf16_f32 v249, v252, v253
	ds_write_b64 v223, v[248:249] offset:40960
	v_lshlrev_b32_e32 v236, 16, v188
	v_and_b32_e32 v237, 0xffff0000, v188
	v_lshlrev_b32_e32 v238, 16, v189
	v_and_b32_e32 v239, 0xffff0000, v189
	v_lshlrev_b32_e32 v240, 16, v186
	v_and_b32_e32 v241, 0xffff0000, v186
	v_lshlrev_b32_e32 v242, 16, v187
	v_and_b32_e32 v243, 0xffff0000, v187
	v_lshlrev_b32_e32 v244, 16, v190
	v_and_b32_e32 v245, 0xffff0000, v190
	v_lshlrev_b32_e32 v246, 16, v191
	v_and_b32_e32 v247, 0xffff0000, v191
	v_pk_mul_f32 v[236:237], v[236:237], v[128:129]
	v_pk_mul_f32 v[238:239], v[238:239], v[130:131]
	v_pk_fma_f32 v[248:249], v[132:133], v[240:241], v[236:237]
	v_pk_fma_f32 v[236:237], v[134:135], v[242:243], v[238:239]
	v_pk_fma_f32 v[248:249], v[244:245], v[136:137], v[248:249]
	v_pk_fma_f32 v[236:237], v[246:247], v[138:139], v[236:237]
	v_pk_add_f32 v[248:249], v[140:141], v[248:249]
	v_pk_add_f32 v[236:237], v[142:143], v[236:237]
	v_pk_mul_f32 v[250:251], v[248:249], v[248:249]
	v_pk_mul_f32 v[252:253], v[236:237], v[236:237]
	v_pk_fma_f32 v[250:251], v[250:251], s[96:97], v[232:233] op_sel_hi:[1,0,1]
	v_pk_fma_f32 v[252:253], v[252:253], s[96:97], v[232:233] op_sel_hi:[1,0,1]
	v_pk_mul_f32 v[250:251], v[248:249], v[250:251]
	v_pk_mul_f32 v[252:253], v[236:237], v[252:253]
	v_exp_f32_e32 v250, v250
	v_exp_f32_e32 v251, v251
	v_exp_f32_e32 v252, v252
	v_exp_f32_e32 v253, v253
	v_pk_add_f32 v[250:251], v[250:251], 1.0 op_sel_hi:[1,0]
	v_pk_add_f32 v[252:253], v[252:253], 1.0 op_sel_hi:[1,0]
	v_rcp_f32_e32 v250, v250
	v_rcp_f32_e32 v251, v251
	v_rcp_f32_e32 v252, v252
	v_rcp_f32_e32 v253, v253
	v_pk_fma_f32 v[250:251], v[248:249], v[250:251], v[248:249] neg_lo:[1,0,0] neg_hi:[1,0,0]
	v_pk_fma_f32 v[252:253], v[236:237], v[252:253], v[236:237] neg_lo:[1,0,0] neg_hi:[1,0,0]
	v_pk_mul_f32 v[250:251], v[76:77], v[250:251]
	v_pk_mul_f32 v[252:253], v[78:79], v[252:253]
	v_cvt_pk_bf16_f32 v248, v250, v251
	v_cvt_pk_bf16_f32 v249, v252, v253
	ds_write_b64 v222, v[248:249] offset:49408
	v_lshlrev_b32_e32 v236, 16, v194
	v_and_b32_e32 v237, 0xffff0000, v194
	v_lshlrev_b32_e32 v238, 16, v195
	v_and_b32_e32 v239, 0xffff0000, v195
	v_lshlrev_b32_e32 v240, 16, v192
	v_and_b32_e32 v241, 0xffff0000, v192
	v_lshlrev_b32_e32 v242, 16, v193
	v_and_b32_e32 v243, 0xffff0000, v193
	v_lshlrev_b32_e32 v244, 16, v196
	v_and_b32_e32 v245, 0xffff0000, v196
	v_lshlrev_b32_e32 v246, 16, v197
	v_and_b32_e32 v247, 0xffff0000, v197
	v_pk_mul_f32 v[236:237], v[236:237], v[144:145]
	v_pk_mul_f32 v[238:239], v[238:239], v[146:147]
	v_pk_fma_f32 v[248:249], v[148:149], v[240:241], v[236:237]
	v_pk_fma_f32 v[236:237], v[150:151], v[242:243], v[238:239]
	v_pk_fma_f32 v[248:249], v[244:245], v[152:153], v[248:249]
	v_pk_fma_f32 v[236:237], v[246:247], v[154:155], v[236:237]
	v_pk_add_f32 v[248:249], v[156:157], v[248:249]
	v_pk_add_f32 v[236:237], v[158:159], v[236:237]
	v_pk_mul_f32 v[250:251], v[248:249], v[248:249]
	v_pk_mul_f32 v[252:253], v[236:237], v[236:237]
	v_pk_fma_f32 v[250:251], v[250:251], s[96:97], v[232:233] op_sel_hi:[1,0,1]
	v_pk_fma_f32 v[252:253], v[252:253], s[96:97], v[232:233] op_sel_hi:[1,0,1]
	v_pk_mul_f32 v[250:251], v[248:249], v[250:251]
	v_pk_mul_f32 v[252:253], v[236:237], v[252:253]
	v_exp_f32_e32 v250, v250
	v_exp_f32_e32 v251, v251
	v_exp_f32_e32 v252, v252
	v_exp_f32_e32 v253, v253
; #define PUT(val) *(uint2*)(g_smem + est_off(rl_, cl)) = pack4(val)
; __device__ __forceinline__ void gemm_epi(const Job& J, f32x4 (&acc)[2][2][4][2], int brow, int bcol, int wvs) {
;     ...
;         PUT(o); }), ({ *(u32x4*)(C + (long)R * ldc + Cc) = LDV; })) } break;
	v_pk_add_f32 v[250:251], v[250:251], 1.0 op_sel_hi:[1,0]
	v_pk_add_f32 v[252:253], v[252:253], 1.0 op_sel_hi:[1,0]
	v_rcp_f32_e32 v250, v250
	v_rcp_f32_e32 v251, v251
	v_rcp_f32_e32 v252, v252
	v_rcp_f32_e32 v253, v253
	v_pk_fma_f32 v[250:251], v[248:249], v[250:251], v[248:249] neg_lo:[1,0,0] neg_hi:[1,0,0]
	v_pk_fma_f32 v[252:253], v[236:237], v[252:253], v[236:237] neg_lo:[1,0,0] neg_hi:[1,0,0]
	v_pk_mul_f32 v[250:251], v[72:73], v[250:251]
	v_pk_mul_f32 v[252:253], v[74:75], v[252:253]
	v_cvt_pk_bf16_f32 v248, v250, v251
	v_cvt_pk_bf16_f32 v249, v252, v253
	ds_write_b64 v223, v[248:249] offset:49408
	v_lshlrev_b32_e32 v236, 16, v200
	v_and_b32_e32 v237, 0xffff0000, v200
	v_lshlrev_b32_e32 v238, 16, v201
	v_and_b32_e32 v239, 0xffff0000, v201
	v_lshlrev_b32_e32 v240, 16, v198
	v_and_b32_e32 v241, 0xffff0000, v198
	v_lshlrev_b32_e32 v242, 16, v199
	v_and_b32_e32 v243, 0xffff0000, v199
	v_lshlrev_b32_e32 v244, 16, v202
	v_and_b32_e32 v245, 0xffff0000, v202
	v_lshlrev_b32_e32 v246, 16, v203
	v_and_b32_e32 v247, 0xffff0000, v203
	v_pk_mul_f32 v[236:237], v[236:237], v[128:129]
	v_pk_mul_f32 v[238:239], v[238:239], v[130:131]
	v_pk_fma_f32 v[248:249], v[132:133], v[240:241], v[236:237]
	v_pk_fma_f32 v[236:237], v[134:135], v[242:243], v[238:239]
	v_pk_fma_f32 v[248:249], v[244:245], v[136:137], v[248:249]
	v_pk_fma_f32 v[236:237], v[246:247], v[138:139], v[236:237]
	v_pk_add_f32 v[248:249], v[140:141], v[248:249]
	v_pk_add_f32 v[236:237], v[142:143], v[236:237]
	v_pk_mul_f32 v[250:251], v[248:249], v[248:249]
	v_pk_mul_f32 v[252:253], v[236:237], v[236:237]
	v_pk_fma_f32 v[250:251], v[250:251], s[96:97], v[232:233] op_sel_hi:[1,0,1]
	v_pk_fma_f32 v[252:253], v[252:253], s[96:97], v[232:233] op_sel_hi:[1,0,1]
	v_pk_mul_f32 v[250:251], v[248:249], v[250:251]
	v_pk_mul_f32 v[252:253], v[236:237], v[252:253]
	v_exp_f32_e32 v250, v250
	v_exp_f32_e32 v251, v251
	v_exp_f32_e32 v252, v252
	v_exp_f32_e32 v253, v253
	v_pk_add_f32 v[250:251], v[250:251], 1.0 op_sel_hi:[1,0]
	v_pk_add_f32 v[252:253], v[252:253], 1.0 op_sel_hi:[1,0]
	v_rcp_f32_e32 v250, v250
	v_rcp_f32_e32 v251, v251
	v_rcp_f32_e32 v252, v252
	v_rcp_f32_e32 v253, v253
	v_pk_fma_f32 v[250:251], v[248:249], v[250:251], v[248:249] neg_lo:[1,0,0] neg_hi:[1,0,0]
	v_pk_fma_f32 v[252:253], v[236:237], v[252:253], v[236:237] neg_lo:[1,0,0] neg_hi:[1,0,0]
	v_pk_mul_f32 v[250:251], v[68:69], v[250:251]
	v_pk_mul_f32 v[252:253], v[70:71], v[252:253]
	v_cvt_pk_bf16_f32 v248, v250, v251
	v_cvt_pk_bf16_f32 v249, v252, v253
	ds_write_b64 v222, v[248:249] offset:57344
	v_lshlrev_b32_e32 v236, 16, v216
	v_and_b32_e32 v237, 0xffff0000, v216
	v_lshlrev_b32_e32 v238, 16, v217
	v_and_b32_e32 v239, 0xffff0000, v217
	v_lshlrev_b32_e32 v240, 16, v214
	v_and_b32_e32 v241, 0xffff0000, v214
	v_lshlrev_b32_e32 v242, 16, v215
	v_and_b32_e32 v243, 0xffff0000, v215
	v_lshlrev_b32_e32 v244, 16, v218
	v_and_b32_e32 v245, 0xffff0000, v218
	v_lshlrev_b32_e32 v246, 16, v219
	v_and_b32_e32 v247, 0xffff0000, v219
	v_pk_mul_f32 v[236:237], v[236:237], v[144:145]
	v_pk_mul_f32 v[238:239], v[238:239], v[146:147]
	v_pk_fma_f32 v[248:249], v[148:149], v[240:241], v[236:237]
	v_pk_fma_f32 v[236:237], v[150:151], v[242:243], v[238:239]
	v_pk_fma_f32 v[248:249], v[244:245], v[152:153], v[248:249]
	v_pk_fma_f32 v[236:237], v[246:247], v[154:155], v[236:237]
	v_pk_add_f32 v[248:249], v[156:157], v[248:249]
	v_pk_add_f32 v[236:237], v[158:159], v[236:237]
	v_pk_mul_f32 v[250:251], v[248:249], v[248:249]
	v_pk_mul_f32 v[252:253], v[236:237], v[236:237]
	v_pk_fma_f32 v[250:251], v[250:251], s[96:97], v[232:233] op_sel_hi:[1,0,1]
	v_pk_fma_f32 v[252:253], v[252:253], s[96:97], v[232:233] op_sel_hi:[1,0,1]
	v_pk_mul_f32 v[250:251], v[248:249], v[250:251]
	v_pk_mul_f32 v[252:253], v[236:237], v[252:253]
	v_exp_f32_e32 v250, v250
	v_exp_f32_e32 v251, v251
	v_exp_f32_e32 v252, v252
	v_exp_f32_e32 v253, v253
	v_pk_add_f32 v[250:251], v[250:251], 1.0 op_sel_hi:[1,0]
	v_pk_add_f32 v[252:253], v[252:253], 1.0 op_sel_hi:[1,0]
	v_rcp_f32_e32 v250, v250
	v_rcp_f32_e32 v251, v251
	v_rcp_f32_e32 v252, v252
	v_rcp_f32_e32 v253, v253
	v_pk_fma_f32 v[250:251], v[248:249], v[250:251], v[248:249] neg_lo:[1,0,0] neg_hi:[1,0,0]
	v_pk_fma_f32 v[252:253], v[236:237], v[252:253], v[236:237] neg_lo:[1,0,0] neg_hi:[1,0,0]
	v_pk_mul_f32 v[250:251], v[64:65], v[250:251]
	v_pk_mul_f32 v[252:253], v[66:67], v[252:253]
	v_cvt_pk_bf16_f32 v248, v250, v251
	v_cvt_pk_bf16_f32 v249, v252, v253
	ds_write_b64 v223, v[248:249] offset:57344
	s_waitcnt lgkmcnt(0)
	s_barrier
	v_add_u32_e32 v99, s69, v210
	v_lshrrev_b32_e32 v99, 5, v99
	v_and_b32_e32 v98, 31, v210
	v_xor_b32_e32 v96, v98, v99
	v_lshlrev_b32_e32 v96, 4, v96
	v_xor_b32_e32 v97, 0x100, v96
	v_lshl_add_u32 v96, v99, 9, v96
	v_lshl_add_u32 v97, v99, 9, v97
	v_mul_u32_u24_e32 v99, s4, v99
	v_lshlrev_b32_e32 v98, 4, v98
	v_lshl_add_u32 v98, v99, 1, v98
	s_mul_i32 s6, s90, s4
	s_add_i32 s6, s6, s22
	s_lshl_b32 s6, s6, 1
	s_add_u32 s6, s26, s6
	s_addc_u32 s7, s27, 0
	s_lshl_b32 s8, s4, 5
	ds_read_b128 v[64:67], v96 offset:32768
	ds_read_b128 v[68:71], v97 offset:40960
	ds_read_b128 v[72:75], v96 offset:49152
	ds_read_b128 v[76:79], v97 offset:57344
	v_add_u32_e32 v96, 0x10000, v96
	v_add_u32_e32 v97, 0x10000, v97
	ds_read_b128 v[80:83], v96 offset:32768
	ds_read_b128 v[84:87], v97 offset:40960
	ds_read_b128 v[88:91], v96 offset:49152
	ds_read_b128 v[92:95], v97 offset:57344
	s_waitcnt lgkmcnt(7)
	global_store_dwordx4 v98, v[64:67], s[6:7]
	s_add_u32 s6, s6, s8
	s_addc_u32 s7, s7, 0
	s_waitcnt lgkmcnt(6)
	global_store_dwordx4 v98, v[68:71], s[6:7]
	s_add_u32 s6, s6, s8
	s_addc_u32 s7, s7, 0
	s_waitcnt lgkmcnt(5)
	global_store_dwordx4 v98, v[72:75], s[6:7]
	s_add_u32 s6, s6, s8
	s_addc_u32 s7, s7, 0
	s_waitcnt lgkmcnt(4)
	global_store_dwordx4 v98, v[76:79], s[6:7]
	s_add_u32 s6, s6, s8
	s_addc_u32 s7, s7, 0
	s_waitcnt lgkmcnt(3)
	global_store_dwordx4 v98, v[80:83], s[6:7]
	s_add_u32 s6, s6, s8
	s_addc_u32 s7, s7, 0
	s_waitcnt lgkmcnt(2)
	global_store_dwordx4 v98, v[84:87], s[6:7]
	s_add_u32 s6, s6, s8
	s_addc_u32 s7, s7, 0
	s_waitcnt lgkmcnt(1)
	global_store_dwordx4 v98, v[88:91], s[6:7]
	s_add_u32 s6, s6, s8
	s_addc_u32 s7, s7, 0
	s_waitcnt lgkmcnt(0)
	global_store_dwordx4 v98, v[92:95], s[6:7]
	s_waitcnt lgkmcnt(0)
	s_barrier
; #define PUT(val) *(uint2*)(g_smem + est_off(rl_, cl)) = pack4(val)
; #define STAGED2(WBODY, SBODY) { { constexpr int AIV = 0; (void)AIV; HLOOP(0, WBODY) __syncthreads(); WLOOP(0, SBODY) } __syncthreads(); { constexpr int AIV = 1; (void)AIV; HLOOP(1, WBODY) __syncthreads(); WLOOP(1, SBODY) } }
; __device__ __forceinline__ float gelu_tanh(float x) {
;   float u = 0.7978845608028654f * (x + 0.044715f * x * x * x);
;   float e = __expf(2.f * u);
;   float t = 1.f - 2.f * __builtin_amdgcn_rcpf(e + 1.f);
;   return 0.5f * x * (1.f + t);
; }
; __device__ __forceinline__ void gemm_epi(const Job& J, f32x4 (&acc)[2][2][4][2], int brow, int bcol, int wvs) {
;     ...
;     STAGED2(({ int pos = R & ((1 << lg) - 1); const u16* gp = G + (long)R * DFF + Cc;
;         f32x4 g0 = unpack4(*(const uint2*)gp), gm = {0.f, 0.f, 0.f, 0.f}, gn = {0.f, 0.f, 0.f, 0.f};
;         if (pos > 0) gm = unpack4(*(const uint2*)(gp - DFF));
;         if (pos < (1 << lg) - 1) gn = unpack4(*(const uint2*)(gp + DFF));
;         f32x4 w0 = *(const f32x4*)(cw + Cc), w1 = *(const f32x4*)(cw + DFF + Cc), w2 = *(const f32x4*)(cw + 2 * DFF + Cc), bb = *(const f32x4*)(cb + Cc);
;         f32x4 o; _Pragma("unroll") for (int j = 0; j < 4; ++j) { float cv = gm[j] * w0[j] + g0[j] * w1[j] + gn[j] * w2[j] + bb[j]; o[j] = gelu_tanh(cv) * v[j]; }
;         PUT(o); }), ({ *(u32x4*)(C + (long)R * ldc + Cc) = LDV; })) } break;
	global_load_dwordx4 v[128:131], v220, s[12:13] offset:0
	global_load_dwordx4 v[132:135], v220, s[18:19] offset:0
	global_load_dwordx4 v[136:139], v220, s[20:21] offset:0
	global_load_dwordx4 v[140:143], v220, s[10:11] offset:0
	global_load_dwordx4 v[144:147], v220, s[12:13] offset:64
	global_load_dwordx4 v[148:151], v220, s[18:19] offset:64
	global_load_dwordx4 v[152:155], v220, s[20:21] offset:64
	global_load_dwordx4 v[156:159], v220, s[10:11] offset:64
	v_add_u32_e32 v225, 0x160000, v221
	global_load_dwordx2 v[162:163], v225, s[46:47] offset:0
	global_load_dwordx2 v[164:165], v225, s[14:15] offset:0
	global_load_dwordx2 v[166:167], v225, s[16:17] offset:0
	global_load_dwordx2 v[168:169], v225, s[46:47] offset:32
	global_load_dwordx2 v[170:171], v225, s[14:15] offset:32
	global_load_dwordx2 v[172:173], v225, s[16:17] offset:32
	v_add_u32_e32 v225, 0x18c000, v221
	global_load_dwordx2 v[174:175], v225, s[46:47] offset:0
	global_load_dwordx2 v[176:177], v225, s[14:15] offset:0
	global_load_dwordx2 v[178:179], v225, s[16:17] offset:0
	global_load_dwordx2 v[180:181], v225, s[46:47] offset:32
	global_load_dwordx2 v[182:183], v225, s[14:15] offset:32
	global_load_dwordx2 v[184:185], v225, s[16:17] offset:32
	v_add_u32_e32 v225, 0x1b8000, v221
	global_load_dwordx2 v[186:187], v225, s[46:47] offset:0
	global_load_dwordx2 v[188:189], v225, s[14:15] offset:0
	global_load_dwordx2 v[190:191], v225, s[16:17] offset:0
	global_load_dwordx2 v[192:193], v225, s[46:47] offset:32
	global_load_dwordx2 v[194:195], v225, s[14:15] offset:32
	global_load_dwordx2 v[196:197], v225, s[16:17] offset:32
	v_add_u32_e32 v225, 0x1e4000, v221
	global_load_dwordx2 v[198:199], v225, s[46:47] offset:0
	global_load_dwordx2 v[200:201], v225, s[14:15] offset:0
	global_load_dwordx2 v[202:203], v225, s[16:17] offset:0
	global_load_dwordx2 v[214:215], v225, s[46:47] offset:32
	global_load_dwordx2 v[216:217], v225, s[14:15] offset:32
	global_load_dwordx2 v[218:219], v225, s[16:17] offset:32
	s_waitcnt vmcnt(0)
	v_lshlrev_b32_e32 v236, 16, v164
	v_and_b32_e32 v237, 0xffff0000, v164
	v_lshlrev_b32_e32 v238, 16, v165
	v_and_b32_e32 v239, 0xffff0000, v165
	v_lshlrev_b32_e32 v240, 16, v162
	v_and_b32_e32 v241, 0xffff0000, v162
	v_lshlrev_b32_e32 v242, 16, v163
	v_and_b32_e32 v243, 0xffff0000, v163
	v_lshlrev_b32_e32 v244, 16, v166
	v_and_b32_e32 v245, 0xffff0000, v166
	v_lshlrev_b32_e32 v246, 16, v167
	v_and_b32_e32 v247, 0xffff0000, v167
	v_pk_mul_f32 v[236:237], v[236:237], v[128:129]
	v_pk_mul_f32 v[238:239], v[238:239], v[130:131]
	v_pk_fma_f32 v[248:249], v[132:133], v[240:241], v[236:237]
	v_pk_fma_f32 v[236:237], v[134:135], v[242:243], v[238:239]
	v_pk_fma_f32 v[248:249], v[244:245], v[136:137], v[248:249]
	v_pk_fma_f32 v[236:237], v[246:247], v[138:139], v[236:237]
	v_pk_add_f32 v[248:249], v[140:141], v[248:249]
	v_pk_add_f32 v[236:237], v[142:143], v[236:237]
	v_pk_mul_f32 v[250:251], v[248:249], v[248:249]
	v_pk_mul_f32 v[252:253], v[236:237], v[236:237]
	v_pk_fma_f32 v[250:251], v[250:251], s[96:97], v[232:233] op_sel_hi:[1,0,1]
	v_pk_fma_f32 v[252:253], v[252:253], s[96:97], v[232:233] op_sel_hi:[1,0,1]
	v_pk_mul_f32 v[250:251], v[248:249], v[250:251]
	v_pk_mul_f32 v[252:253], v[236:237], v[252:253]
	v_exp_f32_e32 v250, v250
	v_exp_f32_e32 v251, v251
	v_exp_f32_e32 v252, v252
	v_exp_f32_e32 v253, v253
	v_pk_add_f32 v[250:251], v[250:251], 1.0 op_sel_hi:[1,0]
	v_pk_add_f32 v[252:253], v[252:253], 1.0 op_sel_hi:[1,0]
	v_rcp_f32_e32 v250, v250
	v_rcp_f32_e32 v251, v251
	v_rcp_f32_e32 v252, v252
	v_rcp_f32_e32 v253, v253
	v_pk_fma_f32 v[250:251], v[248:249], v[250:251], v[248:249] neg_lo:[1,0,0] neg_hi:[1,0,0]
	v_pk_fma_f32 v[252:253], v[236:237], v[252:253], v[236:237] neg_lo:[1,0,0] neg_hi:[1,0,0]
	v_pk_mul_f32 v[250:251], v[60:61], v[250:251]
	v_pk_mul_f32 v[252:253], v[62:63], v[252:253]
	v_cvt_pk_bf16_f32 v248, v250, v251
	v_cvt_pk_bf16_f32 v249, v252, v253
	ds_write_b64 v222, v[248:249] offset:32768
	v_lshlrev_b32_e32 v236, 16, v170
	v_and_b32_e32 v237, 0xffff0000, v170
	v_lshlrev_b32_e32 v238, 16, v171
	v_and_b32_e32 v239, 0xffff0000, v171
	v_lshlrev_b32_e32 v240, 16, v168
	v_and_b32_e32 v241, 0xffff0000, v168
	v_lshlrev_b32_e32 v242, 16, v169
	v_and_b32_e32 v243, 0xffff0000, v169
	v_lshlrev_b32_e32 v244, 16, v172
	v_and_b32_e32 v245, 0xffff0000, v172
	v_lshlrev_b32_e32 v246, 16, v173
	v_and_b32_e32 v247, 0xffff0000, v173
	v_pk_mul_f32 v[236:237], v[236:237], v[144:145]
	v_pk_mul_f32 v[238:239], v[238:239], v[146:147]
	v_pk_fma_f32 v[248:249], v[148:149], v[240:241], v[236:237]
	v_pk_fma_f32 v[236:237], v[150:151], v[242:243], v[238:239]
	v_pk_fma_f32 v[248:249], v[244:245], v[152:153], v[248:249]
	v_pk_fma_f32 v[236:237], v[246:247], v[154:155], v[236:237]
	v_pk_add_f32 v[248:249], v[156:157], v[248:249]
	v_pk_add_f32 v[236:237], v[158:159], v[236:237]
	v_pk_mul_f32 v[250:251], v[248:249], v[248:249]
	v_pk_mul_f32 v[252:253], v[236:237], v[236:237]
	v_pk_fma_f32 v[250:251], v[250:251], s[96:97], v[232:233] op_sel_hi:[1,0,1]
	v_pk_fma_f32 v[252:253], v[252:253], s[96:97], v[232:233] op_sel_hi:[1,0,1]
	v_pk_mul_f32 v[250:251], v[248:249], v[250:251]
	v_pk_mul_f32 v[252:253], v[236:237], v[252:253]
	v_exp_f32_e32 v250, v250
	v_exp_f32_e32 v251, v251
	v_exp_f32_e32 v252, v252
	v_exp_f32_e32 v253, v253
	v_pk_add_f32 v[250:251], v[250:251], 1.0 op_sel_hi:[1,0]
	v_pk_add_f32 v[252:253], v[252:253], 1.0 op_sel_hi:[1,0]
	v_rcp_f32_e32 v250, v250
	v_rcp_f32_e32 v251, v251
	v_rcp_f32_e32 v252, v252
	v_rcp_f32_e32 v253, v253
	v_pk_fma_f32 v[250:251], v[248:249], v[250:251], v[248:249] neg_lo:[1,0,0] neg_hi:[1,0,0]
	v_pk_fma_f32 v[252:253], v[236:237], v[252:253], v[236:237] neg_lo:[1,0,0] neg_hi:[1,0,0]
; #define PUT(val) *(uint2*)(g_smem + est_off(rl_, cl)) = pack4(val)
; #define STAGED2(WBODY, SBODY) { { constexpr int AIV = 0; (void)AIV; HLOOP(0, WBODY) __syncthreads(); WLOOP(0, SBODY) } __syncthreads(); { constexpr int AIV = 1; (void)AIV; HLOOP(1, WBODY) __syncthreads(); WLOOP(1, SBODY) } }
; __device__ __forceinline__ float gelu_tanh(float x) {
;   float u = 0.7978845608028654f * (x + 0.044715f * x * x * x);
;   float e = __expf(2.f * u);
;   float t = 1.f - 2.f * __builtin_amdgcn_rcpf(e + 1.f);
;   return 0.5f * x * (1.f + t);
; }
; __device__ __forceinline__ void gemm_epi(const Job& J, f32x4 (&acc)[2][2][4][2], int brow, int bcol, int wvs) {
;     ...
;     STAGED2(({ int pos = R & ((1 << lg) - 1); const u16* gp = G + (long)R * DFF + Cc;
;         f32x4 g0 = unpack4(*(const uint2*)gp), gm = {0.f, 0.f, 0.f, 0.f}, gn = {0.f, 0.f, 0.f, 0.f};
;         if (pos > 0) gm = unpack4(*(const uint2*)(gp - DFF));
;         if (pos < (1 << lg) - 1) gn = unpack4(*(const uint2*)(gp + DFF));
;         f32x4 w0 = *(const f32x4*)(cw + Cc), w1 = *(const f32x4*)(cw + DFF + Cc), w2 = *(const f32x4*)(cw + 2 * DFF + Cc), bb = *(const f32x4*)(cb + Cc);
;         f32x4 o; _Pragma("unroll") for (int j = 0; j < 4; ++j) { float cv = gm[j] * w0[j] + g0[j] * w1[j] + gn[j] * w2[j] + bb[j]; o[j] = gelu_tanh(cv) * v[j]; }
;         PUT(o); }), ({ *(u32x4*)(C + (long)R * ldc + Cc) = LDV; })) } break;
	v_pk_mul_f32 v[250:251], v[56:57], v[250:251]
	v_pk_mul_f32 v[252:253], v[58:59], v[252:253]
	v_cvt_pk_bf16_f32 v248, v250, v251
	v_cvt_pk_bf16_f32 v249, v252, v253
	ds_write_b64 v223, v[248:249] offset:32768
	v_lshlrev_b32_e32 v236, 16, v176
	v_and_b32_e32 v237, 0xffff0000, v176
	v_lshlrev_b32_e32 v238, 16, v177
	v_and_b32_e32 v239, 0xffff0000, v177
	v_lshlrev_b32_e32 v240, 16, v174
	v_and_b32_e32 v241, 0xffff0000, v174
	v_lshlrev_b32_e32 v242, 16, v175
	v_and_b32_e32 v243, 0xffff0000, v175
	v_lshlrev_b32_e32 v244, 16, v178
	v_and_b32_e32 v245, 0xffff0000, v178
	v_lshlrev_b32_e32 v246, 16, v179
	v_and_b32_e32 v247, 0xffff0000, v179
	v_pk_mul_f32 v[236:237], v[236:237], v[128:129]
	v_pk_mul_f32 v[238:239], v[238:239], v[130:131]
	v_pk_fma_f32 v[248:249], v[132:133], v[240:241], v[236:237]
	v_pk_fma_f32 v[236:237], v[134:135], v[242:243], v[238:239]
	v_pk_fma_f32 v[248:249], v[244:245], v[136:137], v[248:249]
	v_pk_fma_f32 v[236:237], v[246:247], v[138:139], v[236:237]
	v_pk_add_f32 v[248:249], v[140:141], v[248:249]
	v_pk_add_f32 v[236:237], v[142:143], v[236:237]
	v_pk_mul_f32 v[250:251], v[248:249], v[248:249]
	v_pk_mul_f32 v[252:253], v[236:237], v[236:237]
	v_pk_fma_f32 v[250:251], v[250:251], s[96:97], v[232:233] op_sel_hi:[1,0,1]
	v_pk_fma_f32 v[252:253], v[252:253], s[96:97], v[232:233] op_sel_hi:[1,0,1]
	v_pk_mul_f32 v[250:251], v[248:249], v[250:251]
	v_pk_mul_f32 v[252:253], v[236:237], v[252:253]
	v_exp_f32_e32 v250, v250
	v_exp_f32_e32 v251, v251
	v_exp_f32_e32 v252, v252
	v_exp_f32_e32 v253, v253
	v_pk_add_f32 v[250:251], v[250:251], 1.0 op_sel_hi:[1,0]
	v_pk_add_f32 v[252:253], v[252:253], 1.0 op_sel_hi:[1,0]
	v_rcp_f32_e32 v250, v250
	v_rcp_f32_e32 v251, v251
	v_rcp_f32_e32 v252, v252
	v_rcp_f32_e32 v253, v253
	v_pk_fma_f32 v[250:251], v[248:249], v[250:251], v[248:249] neg_lo:[1,0,0] neg_hi:[1,0,0]
	v_pk_fma_f32 v[252:253], v[236:237], v[252:253], v[236:237] neg_lo:[1,0,0] neg_hi:[1,0,0]
	v_pk_mul_f32 v[250:251], v[52:53], v[250:251]
	v_pk_mul_f32 v[252:253], v[54:55], v[252:253]
	v_cvt_pk_bf16_f32 v248, v250, v251
	v_cvt_pk_bf16_f32 v249, v252, v253
	ds_write_b64 v222, v[248:249] offset:41216
	v_lshlrev_b32_e32 v236, 16, v182
	v_and_b32_e32 v237, 0xffff0000, v182
	v_lshlrev_b32_e32 v238, 16, v183
	v_and_b32_e32 v239, 0xffff0000, v183
	v_lshlrev_b32_e32 v240, 16, v180
	v_and_b32_e32 v241, 0xffff0000, v180
	v_lshlrev_b32_e32 v242, 16, v181
	v_and_b32_e32 v243, 0xffff0000, v181
	v_lshlrev_b32_e32 v244, 16, v184
	v_and_b32_e32 v245, 0xffff0000, v184
	v_lshlrev_b32_e32 v246, 16, v185
	v_and_b32_e32 v247, 0xffff0000, v185
	v_pk_mul_f32 v[236:237], v[236:237], v[144:145]
	v_pk_mul_f32 v[238:239], v[238:239], v[146:147]
	v_pk_fma_f32 v[248:249], v[148:149], v[240:241], v[236:237]
	v_pk_fma_f32 v[236:237], v[150:151], v[242:243], v[238:239]
	v_pk_fma_f32 v[248:249], v[244:245], v[152:153], v[248:249]
	v_pk_fma_f32 v[236:237], v[246:247], v[154:155], v[236:237]
	v_pk_add_f32 v[248:249], v[156:157], v[248:249]
	v_pk_add_f32 v[236:237], v[158:159], v[236:237]
	v_pk_mul_f32 v[250:251], v[248:249], v[248:249]
	v_pk_mul_f32 v[252:253], v[236:237], v[236:237]
	v_pk_fma_f32 v[250:251], v[250:251], s[96:97], v[232:233] op_sel_hi:[1,0,1]
	v_pk_fma_f32 v[252:253], v[252:253], s[96:97], v[232:233] op_sel_hi:[1,0,1]
	v_pk_mul_f32 v[250:251], v[248:249], v[250:251]
	v_pk_mul_f32 v[252:253], v[236:237], v[252:253]
	v_exp_f32_e32 v250, v250
	v_exp_f32_e32 v251, v251
	v_exp_f32_e32 v252, v252
	v_exp_f32_e32 v253, v253
	v_pk_add_f32 v[250:251], v[250:251], 1.0 op_sel_hi:[1,0]
	v_pk_add_f32 v[252:253], v[252:253], 1.0 op_sel_hi:[1,0]
	v_rcp_f32_e32 v250, v250
	v_rcp_f32_e32 v251, v251
	v_rcp_f32_e32 v252, v252
	v_rcp_f32_e32 v253, v253
	v_pk_fma_f32 v[250:251], v[248:249], v[250:251], v[248:249] neg_lo:[1,0,0] neg_hi:[1,0,0]
	v_pk_fma_f32 v[252:253], v[236:237], v[252:253], v[236:237] neg_lo:[1,0,0] neg_hi:[1,0,0]
	v_pk_mul_f32 v[250:251], v[48:49], v[250:251]
	v_pk_mul_f32 v[252:253], v[50:51], v[252:253]
	v_cvt_pk_bf16_f32 v248, v250, v251
	v_cvt_pk_bf16_f32 v249, v252, v253
	ds_write_b64 v223, v[248:249] offset:41216
	v_lshlrev_b32_e32 v236, 16, v188
	v_and_b32_e32 v237, 0xffff0000, v188
	v_lshlrev_b32_e32 v238, 16, v189
	v_and_b32_e32 v239, 0xffff0000, v189
	v_lshlrev_b32_e32 v240, 16, v186
	v_and_b32_e32 v241, 0xffff0000, v186
	v_lshlrev_b32_e32 v242, 16, v187
	v_and_b32_e32 v243, 0xffff0000, v187
	v_lshlrev_b32_e32 v244, 16, v190
	v_and_b32_e32 v245, 0xffff0000, v190
	v_lshlrev_b32_e32 v246, 16, v191
	v_and_b32_e32 v247, 0xffff0000, v191
	v_pk_mul_f32 v[236:237], v[236:237], v[128:129]
	v_pk_mul_f32 v[238:239], v[238:239], v[130:131]
	v_pk_fma_f32 v[248:249], v[132:133], v[240:241], v[236:237]
	v_pk_fma_f32 v[236:237], v[134:135], v[242:243], v[238:239]
	v_pk_fma_f32 v[248:249], v[244:245], v[136:137], v[248:249]
	v_pk_fma_f32 v[236:237], v[246:247], v[138:139], v[236:237]
	v_pk_add_f32 v[248:249], v[140:141], v[248:249]
	v_pk_add_f32 v[236:237], v[142:143], v[236:237]
	v_pk_mul_f32 v[250:251], v[248:249], v[248:249]
	v_pk_mul_f32 v[252:253], v[236:237], v[236:237]
	v_pk_fma_f32 v[250:251], v[250:251], s[96:97], v[232:233] op_sel_hi:[1,0,1]
	v_pk_fma_f32 v[252:253], v[252:253], s[96:97], v[232:233] op_sel_hi:[1,0,1]
	v_pk_mul_f32 v[250:251], v[248:249], v[250:251]
	v_pk_mul_f32 v[252:253], v[236:237], v[252:253]
	v_exp_f32_e32 v250, v250
	v_exp_f32_e32 v251, v251
	v_exp_f32_e32 v252, v252
	v_exp_f32_e32 v253, v253
	v_pk_add_f32 v[250:251], v[250:251], 1.0 op_sel_hi:[1,0]
	v_pk_add_f32 v[252:253], v[252:253], 1.0 op_sel_hi:[1,0]
	v_rcp_f32_e32 v250, v250
	v_rcp_f32_e32 v251, v251
	v_rcp_f32_e32 v252, v252
	v_rcp_f32_e32 v253, v253
; #define PUT(val) *(uint2*)(g_smem + est_off(rl_, cl)) = pack4(val)
; #define STAGED2(WBODY, SBODY) { { constexpr int AIV = 0; (void)AIV; HLOOP(0, WBODY) __syncthreads(); WLOOP(0, SBODY) } __syncthreads(); { constexpr int AIV = 1; (void)AIV; HLOOP(1, WBODY) __syncthreads(); WLOOP(1, SBODY) } }
; __device__ __forceinline__ float gelu_tanh(float x) {
;   float u = 0.7978845608028654f * (x + 0.044715f * x * x * x);
;   float e = __expf(2.f * u);
;   float t = 1.f - 2.f * __builtin_amdgcn_rcpf(e + 1.f);
;   return 0.5f * x * (1.f + t);
; }
; __device__ __forceinline__ void gemm_epi(const Job& J, f32x4 (&acc)[2][2][4][2], int brow, int bcol, int wvs) {
;     ...
;     STAGED2(({ int pos = R & ((1 << lg) - 1); const u16* gp = G + (long)R * DFF + Cc;
;         f32x4 g0 = unpack4(*(const uint2*)gp), gm = {0.f, 0.f, 0.f, 0.f}, gn = {0.f, 0.f, 0.f, 0.f};
;         if (pos > 0) gm = unpack4(*(const uint2*)(gp - DFF));
;         if (pos < (1 << lg) - 1) gn = unpack4(*(const uint2*)(gp + DFF));
;         f32x4 w0 = *(const f32x4*)(cw + Cc), w1 = *(const f32x4*)(cw + DFF + Cc), w2 = *(const f32x4*)(cw + 2 * DFF + Cc), bb = *(const f32x4*)(cb + Cc);
;         f32x4 o; _Pragma("unroll") for (int j = 0; j < 4; ++j) { float cv = gm[j] * w0[j] + g0[j] * w1[j] + gn[j] * w2[j] + bb[j]; o[j] = gelu_tanh(cv) * v[j]; }
;         PUT(o); }), ({ *(u32x4*)(C + (long)R * ldc + Cc) = LDV; })) } break;
	v_pk_fma_f32 v[250:251], v[248:249], v[250:251], v[248:249] neg_lo:[1,0,0] neg_hi:[1,0,0]
	v_pk_fma_f32 v[252:253], v[236:237], v[252:253], v[236:237] neg_lo:[1,0,0] neg_hi:[1,0,0]
	v_pk_mul_f32 v[250:251], v[44:45], v[250:251]
	v_pk_mul_f32 v[252:253], v[46:47], v[252:253]
	v_cvt_pk_bf16_f32 v248, v250, v251
	v_cvt_pk_bf16_f32 v249, v252, v253
	ds_write_b64 v222, v[248:249] offset:49152
	v_lshlrev_b32_e32 v236, 16, v194
	v_and_b32_e32 v237, 0xffff0000, v194
	v_lshlrev_b32_e32 v238, 16, v195
	v_and_b32_e32 v239, 0xffff0000, v195
	v_lshlrev_b32_e32 v240, 16, v192
	v_and_b32_e32 v241, 0xffff0000, v192
	v_lshlrev_b32_e32 v242, 16, v193
	v_and_b32_e32 v243, 0xffff0000, v193
	v_lshlrev_b32_e32 v244, 16, v196
	v_and_b32_e32 v245, 0xffff0000, v196
	v_lshlrev_b32_e32 v246, 16, v197
	v_and_b32_e32 v247, 0xffff0000, v197
	v_pk_mul_f32 v[236:237], v[236:237], v[144:145]
	v_pk_mul_f32 v[238:239], v[238:239], v[146:147]
	v_pk_fma_f32 v[248:249], v[148:149], v[240:241], v[236:237]
	v_pk_fma_f32 v[236:237], v[150:151], v[242:243], v[238:239]
	v_pk_fma_f32 v[248:249], v[244:245], v[152:153], v[248:249]
	v_pk_fma_f32 v[236:237], v[246:247], v[154:155], v[236:237]
	v_pk_add_f32 v[248:249], v[156:157], v[248:249]
	v_pk_add_f32 v[236:237], v[158:159], v[236:237]
	v_pk_mul_f32 v[250:251], v[248:249], v[248:249]
	v_pk_mul_f32 v[252:253], v[236:237], v[236:237]
	v_pk_fma_f32 v[250:251], v[250:251], s[96:97], v[232:233] op_sel_hi:[1,0,1]
	v_pk_fma_f32 v[252:253], v[252:253], s[96:97], v[232:233] op_sel_hi:[1,0,1]
	v_pk_mul_f32 v[250:251], v[248:249], v[250:251]
	v_pk_mul_f32 v[252:253], v[236:237], v[252:253]
	v_exp_f32_e32 v250, v250
	v_exp_f32_e32 v251, v251
	v_exp_f32_e32 v252, v252
	v_exp_f32_e32 v253, v253
	v_pk_add_f32 v[250:251], v[250:251], 1.0 op_sel_hi:[1,0]
	v_pk_add_f32 v[252:253], v[252:253], 1.0 op_sel_hi:[1,0]
	v_rcp_f32_e32 v250, v250
	v_rcp_f32_e32 v251, v251
	v_rcp_f32_e32 v252, v252
	v_rcp_f32_e32 v253, v253
	v_pk_fma_f32 v[250:251], v[248:249], v[250:251], v[248:249] neg_lo:[1,0,0] neg_hi:[1,0,0]
	v_pk_fma_f32 v[252:253], v[236:237], v[252:253], v[236:237] neg_lo:[1,0,0] neg_hi:[1,0,0]
	v_pk_mul_f32 v[250:251], v[40:41], v[250:251]
	v_pk_mul_f32 v[252:253], v[42:43], v[252:253]
	v_cvt_pk_bf16_f32 v248, v250, v251
	v_cvt_pk_bf16_f32 v249, v252, v253
	ds_write_b64 v223, v[248:249] offset:49152
	v_add_u32_e32 v228, 176, v224
	v_and_b32_e32 v228, s31, v228
	v_cmp_ne_u32_e32 vcc, s31, v228
	s_nop 1
	v_cndmask_b32_e64 v226, 0, -1, vcc
	v_and_b32_e32 v202, v226, v202
	v_and_b32_e32 v203, v226, v203
	v_lshlrev_b32_e32 v236, 16, v200
	v_and_b32_e32 v237, 0xffff0000, v200
	v_lshlrev_b32_e32 v238, 16, v201
	v_and_b32_e32 v239, 0xffff0000, v201
	v_lshlrev_b32_e32 v240, 16, v198
	v_and_b32_e32 v241, 0xffff0000, v198
	v_lshlrev_b32_e32 v242, 16, v199
	v_and_b32_e32 v243, 0xffff0000, v199
	v_lshlrev_b32_e32 v244, 16, v202
	v_and_b32_e32 v245, 0xffff0000, v202
	v_lshlrev_b32_e32 v246, 16, v203
	v_and_b32_e32 v247, 0xffff0000, v203
	v_pk_mul_f32 v[236:237], v[236:237], v[128:129]
	v_pk_mul_f32 v[238:239], v[238:239], v[130:131]
	v_pk_fma_f32 v[248:249], v[132:133], v[240:241], v[236:237]
	v_pk_fma_f32 v[236:237], v[134:135], v[242:243], v[238:239]
	v_pk_fma_f32 v[248:249], v[244:245], v[136:137], v[248:249]
	v_pk_fma_f32 v[236:237], v[246:247], v[138:139], v[236:237]
	v_pk_add_f32 v[248:249], v[140:141], v[248:249]
	v_pk_add_f32 v[236:237], v[142:143], v[236:237]
	v_pk_mul_f32 v[250:251], v[248:249], v[248:249]
	v_pk_mul_f32 v[252:253], v[236:237], v[236:237]
	v_pk_fma_f32 v[250:251], v[250:251], s[96:97], v[232:233] op_sel_hi:[1,0,1]
	v_pk_fma_f32 v[252:253], v[252:253], s[96:97], v[232:233] op_sel_hi:[1,0,1]
	v_pk_mul_f32 v[250:251], v[248:249], v[250:251]
	v_pk_mul_f32 v[252:253], v[236:237], v[252:253]
	v_exp_f32_e32 v250, v250
	v_exp_f32_e32 v251, v251
	v_exp_f32_e32 v252, v252
	v_exp_f32_e32 v253, v253
	v_pk_add_f32 v[250:251], v[250:251], 1.0 op_sel_hi:[1,0]
	v_pk_add_f32 v[252:253], v[252:253], 1.0 op_sel_hi:[1,0]
	v_rcp_f32_e32 v250, v250
	v_rcp_f32_e32 v251, v251
	v_rcp_f32_e32 v252, v252
	v_rcp_f32_e32 v253, v253
	v_pk_fma_f32 v[250:251], v[248:249], v[250:251], v[248:249] neg_lo:[1,0,0] neg_hi:[1,0,0]
	v_pk_fma_f32 v[252:253], v[236:237], v[252:253], v[236:237] neg_lo:[1,0,0] neg_hi:[1,0,0]
	v_pk_mul_f32 v[250:251], v[36:37], v[250:251]
	v_pk_mul_f32 v[252:253], v[38:39], v[252:253]
	v_cvt_pk_bf16_f32 v248, v250, v251
	v_cvt_pk_bf16_f32 v249, v252, v253
	ds_write_b64 v222, v[248:249] offset:57600
	v_and_b32_e32 v218, v226, v218
	v_and_b32_e32 v219, v226, v219
	v_lshlrev_b32_e32 v236, 16, v216
	v_and_b32_e32 v237, 0xffff0000, v216
	v_lshlrev_b32_e32 v238, 16, v217
	v_and_b32_e32 v239, 0xffff0000, v217
	v_lshlrev_b32_e32 v240, 16, v214
	v_and_b32_e32 v241, 0xffff0000, v214
	v_lshlrev_b32_e32 v242, 16, v215
	v_and_b32_e32 v243, 0xffff0000, v215
	v_lshlrev_b32_e32 v244, 16, v218
	v_and_b32_e32 v245, 0xffff0000, v218
	v_lshlrev_b32_e32 v246, 16, v219
	v_and_b32_e32 v247, 0xffff0000, v219
	v_pk_mul_f32 v[236:237], v[236:237], v[144:145]
	v_pk_mul_f32 v[238:239], v[238:239], v[146:147]
	v_pk_fma_f32 v[248:249], v[148:149], v[240:241], v[236:237]
	v_pk_fma_f32 v[236:237], v[150:151], v[242:243], v[238:239]
	v_pk_fma_f32 v[248:249], v[244:245], v[152:153], v[248:249]
	v_pk_fma_f32 v[236:237], v[246:247], v[154:155], v[236:237]
	v_pk_add_f32 v[248:249], v[156:157], v[248:249]
	v_pk_add_f32 v[236:237], v[158:159], v[236:237]
	v_pk_mul_f32 v[250:251], v[248:249], v[248:249]
	v_pk_mul_f32 v[252:253], v[236:237], v[236:237]
	v_pk_fma_f32 v[250:251], v[250:251], s[96:97], v[232:233] op_sel_hi:[1,0,1]
	v_pk_fma_f32 v[252:253], v[252:253], s[96:97], v[232:233] op_sel_hi:[1,0,1]
; #define PUT(val) *(uint2*)(g_smem + est_off(rl_, cl)) = pack4(val)
; #define STAGED2(WBODY, SBODY) { { constexpr int AIV = 0; (void)AIV; HLOOP(0, WBODY) __syncthreads(); WLOOP(0, SBODY) } __syncthreads(); { constexpr int AIV = 1; (void)AIV; HLOOP(1, WBODY) __syncthreads(); WLOOP(1, SBODY) } }
; __device__ __forceinline__ float gelu_tanh(float x) {
;   float u = 0.7978845608028654f * (x + 0.044715f * x * x * x);
;   float e = __expf(2.f * u);
;   float t = 1.f - 2.f * __builtin_amdgcn_rcpf(e + 1.f);
;   return 0.5f * x * (1.f + t);
; }
; __device__ __forceinline__ void gemm_epi(const Job& J, f32x4 (&acc)[2][2][4][2], int brow, int bcol, int wvs) {
;     ...
;     STAGED2(({ int pos = R & ((1 << lg) - 1); const u16* gp = G + (long)R * DFF + Cc;
;         f32x4 g0 = unpack4(*(const uint2*)gp), gm = {0.f, 0.f, 0.f, 0.f}, gn = {0.f, 0.f, 0.f, 0.f};
;         if (pos > 0) gm = unpack4(*(const uint2*)(gp - DFF));
;         if (pos < (1 << lg) - 1) gn = unpack4(*(const uint2*)(gp + DFF));
;         f32x4 w0 = *(const f32x4*)(cw + Cc), w1 = *(const f32x4*)(cw + DFF + Cc), w2 = *(const f32x4*)(cw + 2 * DFF + Cc), bb = *(const f32x4*)(cb + Cc);
;         f32x4 o; _Pragma("unroll") for (int j = 0; j < 4; ++j) { float cv = gm[j] * w0[j] + g0[j] * w1[j] + gn[j] * w2[j] + bb[j]; o[j] = gelu_tanh(cv) * v[j]; }
;         PUT(o); }), ({ *(u32x4*)(C + (long)R * ldc + Cc) = LDV; })) } break;
	v_pk_mul_f32 v[250:251], v[248:249], v[250:251]
	v_pk_mul_f32 v[252:253], v[236:237], v[252:253]
	v_exp_f32_e32 v250, v250
	v_exp_f32_e32 v251, v251
	v_exp_f32_e32 v252, v252
	v_exp_f32_e32 v253, v253
	v_pk_add_f32 v[250:251], v[250:251], 1.0 op_sel_hi:[1,0]
	v_pk_add_f32 v[252:253], v[252:253], 1.0 op_sel_hi:[1,0]
	v_rcp_f32_e32 v250, v250
	v_rcp_f32_e32 v251, v251
	v_rcp_f32_e32 v252, v252
	v_rcp_f32_e32 v253, v253
	v_pk_fma_f32 v[250:251], v[248:249], v[250:251], v[248:249] neg_lo:[1,0,0] neg_hi:[1,0,0]
	v_pk_fma_f32 v[252:253], v[236:237], v[252:253], v[236:237] neg_lo:[1,0,0] neg_hi:[1,0,0]
	v_pk_mul_f32 v[250:251], v[32:33], v[250:251]
	v_pk_mul_f32 v[252:253], v[34:35], v[252:253]
	v_cvt_pk_bf16_f32 v248, v250, v251
	v_cvt_pk_bf16_f32 v249, v252, v253
	ds_write_b64 v223, v[248:249] offset:57600
	global_load_dwordx4 v[128:131], v220, s[12:13] offset:512
	global_load_dwordx4 v[132:135], v220, s[18:19] offset:512
	global_load_dwordx4 v[136:139], v220, s[20:21] offset:512
	global_load_dwordx4 v[140:143], v220, s[10:11] offset:512
	global_load_dwordx4 v[144:147], v220, s[12:13] offset:576
	global_load_dwordx4 v[148:151], v220, s[18:19] offset:576
	global_load_dwordx4 v[152:155], v220, s[20:21] offset:576
	global_load_dwordx4 v[156:159], v220, s[10:11] offset:576
	v_add_u32_e32 v225, 0x160000, v221
	global_load_dwordx2 v[162:163], v225, s[46:47] offset:256
	global_load_dwordx2 v[164:165], v225, s[14:15] offset:256
	global_load_dwordx2 v[166:167], v225, s[16:17] offset:256
	global_load_dwordx2 v[168:169], v225, s[46:47] offset:288
	global_load_dwordx2 v[170:171], v225, s[14:15] offset:288
	global_load_dwordx2 v[172:173], v225, s[16:17] offset:288
	v_add_u32_e32 v225, 0x18c000, v221
	global_load_dwordx2 v[174:175], v225, s[46:47] offset:256
	global_load_dwordx2 v[176:177], v225, s[14:15] offset:256
	global_load_dwordx2 v[178:179], v225, s[16:17] offset:256
	global_load_dwordx2 v[180:181], v225, s[46:47] offset:288
	global_load_dwordx2 v[182:183], v225, s[14:15] offset:288
	global_load_dwordx2 v[184:185], v225, s[16:17] offset:288
	v_add_u32_e32 v225, 0x1b8000, v221
	global_load_dwordx2 v[186:187], v225, s[46:47] offset:256
	global_load_dwordx2 v[188:189], v225, s[14:15] offset:256
	global_load_dwordx2 v[190:191], v225, s[16:17] offset:256
	global_load_dwordx2 v[192:193], v225, s[46:47] offset:288
	global_load_dwordx2 v[194:195], v225, s[14:15] offset:288
	global_load_dwordx2 v[196:197], v225, s[16:17] offset:288
	v_add_u32_e32 v225, 0x1e4000, v221
	global_load_dwordx2 v[198:199], v225, s[46:47] offset:256
	global_load_dwordx2 v[200:201], v225, s[14:15] offset:256
	global_load_dwordx2 v[202:203], v225, s[16:17] offset:256
	global_load_dwordx2 v[214:215], v225, s[46:47] offset:288
	global_load_dwordx2 v[216:217], v225, s[14:15] offset:288
	global_load_dwordx2 v[218:219], v225, s[16:17] offset:288
	s_waitcnt vmcnt(0)
	v_lshlrev_b32_e32 v236, 16, v164
	v_and_b32_e32 v237, 0xffff0000, v164
	v_lshlrev_b32_e32 v238, 16, v165
	v_and_b32_e32 v239, 0xffff0000, v165
	v_lshlrev_b32_e32 v240, 16, v162
	v_and_b32_e32 v241, 0xffff0000, v162
	v_lshlrev_b32_e32 v242, 16, v163
	v_and_b32_e32 v243, 0xffff0000, v163
	v_lshlrev_b32_e32 v244, 16, v166
	v_and_b32_e32 v245, 0xffff0000, v166
	v_lshlrev_b32_e32 v246, 16, v167
	v_and_b32_e32 v247, 0xffff0000, v167
	v_pk_mul_f32 v[236:237], v[236:237], v[128:129]
	v_pk_mul_f32 v[238:239], v[238:239], v[130:131]
	v_pk_fma_f32 v[248:249], v[132:133], v[240:241], v[236:237]
	v_pk_fma_f32 v[236:237], v[134:135], v[242:243], v[238:239]
	v_pk_fma_f32 v[248:249], v[244:245], v[136:137], v[248:249]
	v_pk_fma_f32 v[236:237], v[246:247], v[138:139], v[236:237]
	v_pk_add_f32 v[248:249], v[140:141], v[248:249]
	v_pk_add_f32 v[236:237], v[142:143], v[236:237]
	v_pk_mul_f32 v[250:251], v[248:249], v[248:249]
	v_pk_mul_f32 v[252:253], v[236:237], v[236:237]
	v_pk_fma_f32 v[250:251], v[250:251], s[96:97], v[232:233] op_sel_hi:[1,0,1]
	v_pk_fma_f32 v[252:253], v[252:253], s[96:97], v[232:233] op_sel_hi:[1,0,1]
	v_pk_mul_f32 v[250:251], v[248:249], v[250:251]
	v_pk_mul_f32 v[252:253], v[236:237], v[252:253]
	v_exp_f32_e32 v250, v250
	v_exp_f32_e32 v251, v251
	v_exp_f32_e32 v252, v252
	v_exp_f32_e32 v253, v253
	v_pk_add_f32 v[250:251], v[250:251], 1.0 op_sel_hi:[1,0]
	v_pk_add_f32 v[252:253], v[252:253], 1.0 op_sel_hi:[1,0]
	v_rcp_f32_e32 v250, v250
	v_rcp_f32_e32 v251, v251
	v_rcp_f32_e32 v252, v252
	v_rcp_f32_e32 v253, v253
	v_pk_fma_f32 v[250:251], v[248:249], v[250:251], v[248:249] neg_lo:[1,0,0] neg_hi:[1,0,0]
	v_pk_fma_f32 v[252:253], v[236:237], v[252:253], v[236:237] neg_lo:[1,0,0] neg_hi:[1,0,0]
	v_pk_mul_f32 v[250:251], v[28:29], v[250:251]
	v_pk_mul_f32 v[252:253], v[30:31], v[252:253]
	v_cvt_pk_bf16_f32 v248, v250, v251
	v_cvt_pk_bf16_f32 v249, v252, v253
	ds_write_b64 v222, v[248:249] offset:33024
	v_lshlrev_b32_e32 v236, 16, v170
	v_and_b32_e32 v237, 0xffff0000, v170
	v_lshlrev_b32_e32 v238, 16, v171
	v_and_b32_e32 v239, 0xffff0000, v171
	v_lshlrev_b32_e32 v240, 16, v168
	v_and_b32_e32 v241, 0xffff0000, v168
	v_lshlrev_b32_e32 v242, 16, v169
	v_and_b32_e32 v243, 0xffff0000, v169
	v_lshlrev_b32_e32 v244, 16, v172
	v_and_b32_e32 v245, 0xffff0000, v172
	v_lshlrev_b32_e32 v246, 16, v173
	v_and_b32_e32 v247, 0xffff0000, v173
	v_pk_mul_f32 v[236:237], v[236:237], v[144:145]
	v_pk_mul_f32 v[238:239], v[238:239], v[146:147]
	v_pk_fma_f32 v[248:249], v[148:149], v[240:241], v[236:237]
	v_pk_fma_f32 v[236:237], v[150:151], v[242:243], v[238:239]
	v_pk_fma_f32 v[248:249], v[244:245], v[152:153], v[248:249]
	v_pk_fma_f32 v[236:237], v[246:247], v[154:155], v[236:237]
	v_pk_add_f32 v[248:249], v[156:157], v[248:249]
; #define PUT(val) *(uint2*)(g_smem + est_off(rl_, cl)) = pack4(val)
; #define STAGED2(WBODY, SBODY) { { constexpr int AIV = 0; (void)AIV; HLOOP(0, WBODY) __syncthreads(); WLOOP(0, SBODY) } __syncthreads(); { constexpr int AIV = 1; (void)AIV; HLOOP(1, WBODY) __syncthreads(); WLOOP(1, SBODY) } }
; __device__ __forceinline__ float gelu_tanh(float x) {
;   float u = 0.7978845608028654f * (x + 0.044715f * x * x * x);
;   float e = __expf(2.f * u);
;   float t = 1.f - 2.f * __builtin_amdgcn_rcpf(e + 1.f);
;   return 0.5f * x * (1.f + t);
; }
; __device__ __forceinline__ void gemm_epi(const Job& J, f32x4 (&acc)[2][2][4][2], int brow, int bcol, int wvs) {
;     ...
;     STAGED2(({ int pos = R & ((1 << lg) - 1); const u16* gp = G + (long)R * DFF + Cc;
;         f32x4 g0 = unpack4(*(const uint2*)gp), gm = {0.f, 0.f, 0.f, 0.f}, gn = {0.f, 0.f, 0.f, 0.f};
;         if (pos > 0) gm = unpack4(*(const uint2*)(gp - DFF));
;         if (pos < (1 << lg) - 1) gn = unpack4(*(const uint2*)(gp + DFF));
;         f32x4 w0 = *(const f32x4*)(cw + Cc), w1 = *(const f32x4*)(cw + DFF + Cc), w2 = *(const f32x4*)(cw + 2 * DFF + Cc), bb = *(const f32x4*)(cb + Cc);
;         f32x4 o; _Pragma("unroll") for (int j = 0; j < 4; ++j) { float cv = gm[j] * w0[j] + g0[j] * w1[j] + gn[j] * w2[j] + bb[j]; o[j] = gelu_tanh(cv) * v[j]; }
;         PUT(o); }), ({ *(u32x4*)(C + (long)R * ldc + Cc) = LDV; })) } break;
	v_pk_add_f32 v[236:237], v[158:159], v[236:237]
	v_pk_mul_f32 v[250:251], v[248:249], v[248:249]
	v_pk_mul_f32 v[252:253], v[236:237], v[236:237]
	v_pk_fma_f32 v[250:251], v[250:251], s[96:97], v[232:233] op_sel_hi:[1,0,1]
	v_pk_fma_f32 v[252:253], v[252:253], s[96:97], v[232:233] op_sel_hi:[1,0,1]
	v_pk_mul_f32 v[250:251], v[248:249], v[250:251]
	v_pk_mul_f32 v[252:253], v[236:237], v[252:253]
	v_exp_f32_e32 v250, v250
	v_exp_f32_e32 v251, v251
	v_exp_f32_e32 v252, v252
	v_exp_f32_e32 v253, v253
	v_pk_add_f32 v[250:251], v[250:251], 1.0 op_sel_hi:[1,0]
	v_pk_add_f32 v[252:253], v[252:253], 1.0 op_sel_hi:[1,0]
	v_rcp_f32_e32 v250, v250
	v_rcp_f32_e32 v251, v251
	v_rcp_f32_e32 v252, v252
	v_rcp_f32_e32 v253, v253
	v_pk_fma_f32 v[250:251], v[248:249], v[250:251], v[248:249] neg_lo:[1,0,0] neg_hi:[1,0,0]
	v_pk_fma_f32 v[252:253], v[236:237], v[252:253], v[236:237] neg_lo:[1,0,0] neg_hi:[1,0,0]
	v_pk_mul_f32 v[250:251], v[24:25], v[250:251]
	v_pk_mul_f32 v[252:253], v[26:27], v[252:253]
	v_cvt_pk_bf16_f32 v248, v250, v251
	v_cvt_pk_bf16_f32 v249, v252, v253
	ds_write_b64 v223, v[248:249] offset:33024
	v_lshlrev_b32_e32 v236, 16, v176
	v_and_b32_e32 v237, 0xffff0000, v176
	v_lshlrev_b32_e32 v238, 16, v177
	v_and_b32_e32 v239, 0xffff0000, v177
	v_lshlrev_b32_e32 v240, 16, v174
	v_and_b32_e32 v241, 0xffff0000, v174
	v_lshlrev_b32_e32 v242, 16, v175
	v_and_b32_e32 v243, 0xffff0000, v175
	v_lshlrev_b32_e32 v244, 16, v178
	v_and_b32_e32 v245, 0xffff0000, v178
	v_lshlrev_b32_e32 v246, 16, v179
	v_and_b32_e32 v247, 0xffff0000, v179
	v_pk_mul_f32 v[236:237], v[236:237], v[128:129]
	v_pk_mul_f32 v[238:239], v[238:239], v[130:131]
	v_pk_fma_f32 v[248:249], v[132:133], v[240:241], v[236:237]
	v_pk_fma_f32 v[236:237], v[134:135], v[242:243], v[238:239]
	v_pk_fma_f32 v[248:249], v[244:245], v[136:137], v[248:249]
	v_pk_fma_f32 v[236:237], v[246:247], v[138:139], v[236:237]
	v_pk_add_f32 v[248:249], v[140:141], v[248:249]
	v_pk_add_f32 v[236:237], v[142:143], v[236:237]
	v_pk_mul_f32 v[250:251], v[248:249], v[248:249]
	v_pk_mul_f32 v[252:253], v[236:237], v[236:237]
	v_pk_fma_f32 v[250:251], v[250:251], s[96:97], v[232:233] op_sel_hi:[1,0,1]
	v_pk_fma_f32 v[252:253], v[252:253], s[96:97], v[232:233] op_sel_hi:[1,0,1]
	v_pk_mul_f32 v[250:251], v[248:249], v[250:251]
	v_pk_mul_f32 v[252:253], v[236:237], v[252:253]
	v_exp_f32_e32 v250, v250
	v_exp_f32_e32 v251, v251
	v_exp_f32_e32 v252, v252
	v_exp_f32_e32 v253, v253
	v_pk_add_f32 v[250:251], v[250:251], 1.0 op_sel_hi:[1,0]
	v_pk_add_f32 v[252:253], v[252:253], 1.0 op_sel_hi:[1,0]
	v_rcp_f32_e32 v250, v250
	v_rcp_f32_e32 v251, v251
	v_rcp_f32_e32 v252, v252
	v_rcp_f32_e32 v253, v253
	v_pk_fma_f32 v[250:251], v[248:249], v[250:251], v[248:249] neg_lo:[1,0,0] neg_hi:[1,0,0]
	v_pk_fma_f32 v[252:253], v[236:237], v[252:253], v[236:237] neg_lo:[1,0,0] neg_hi:[1,0,0]
	v_pk_mul_f32 v[250:251], v[20:21], v[250:251]
	v_pk_mul_f32 v[252:253], v[22:23], v[252:253]
	v_cvt_pk_bf16_f32 v248, v250, v251
	v_cvt_pk_bf16_f32 v249, v252, v253
	ds_write_b64 v222, v[248:249] offset:40960
	v_lshlrev_b32_e32 v236, 16, v182
	v_and_b32_e32 v237, 0xffff0000, v182
	v_lshlrev_b32_e32 v238, 16, v183
	v_and_b32_e32 v239, 0xffff0000, v183
	v_lshlrev_b32_e32 v240, 16, v180
	v_and_b32_e32 v241, 0xffff0000, v180
	v_lshlrev_b32_e32 v242, 16, v181
	v_and_b32_e32 v243, 0xffff0000, v181
	v_lshlrev_b32_e32 v244, 16, v184
	v_and_b32_e32 v245, 0xffff0000, v184
	v_lshlrev_b32_e32 v246, 16, v185
	v_and_b32_e32 v247, 0xffff0000, v185
	v_pk_mul_f32 v[236:237], v[236:237], v[144:145]
	v_pk_mul_f32 v[238:239], v[238:239], v[146:147]
	v_pk_fma_f32 v[248:249], v[148:149], v[240:241], v[236:237]
	v_pk_fma_f32 v[236:237], v[150:151], v[242:243], v[238:239]
	v_pk_fma_f32 v[248:249], v[244:245], v[152:153], v[248:249]
	v_pk_fma_f32 v[236:237], v[246:247], v[154:155], v[236:237]
	v_pk_add_f32 v[248:249], v[156:157], v[248:249]
	v_pk_add_f32 v[236:237], v[158:159], v[236:237]
	v_pk_mul_f32 v[250:251], v[248:249], v[248:249]
	v_pk_mul_f32 v[252:253], v[236:237], v[236:237]
	v_pk_fma_f32 v[250:251], v[250:251], s[96:97], v[232:233] op_sel_hi:[1,0,1]
	v_pk_fma_f32 v[252:253], v[252:253], s[96:97], v[232:233] op_sel_hi:[1,0,1]
	v_pk_mul_f32 v[250:251], v[248:249], v[250:251]
	v_pk_mul_f32 v[252:253], v[236:237], v[252:253]
	v_exp_f32_e32 v250, v250
	v_exp_f32_e32 v251, v251
	v_exp_f32_e32 v252, v252
	v_exp_f32_e32 v253, v253
	v_pk_add_f32 v[250:251], v[250:251], 1.0 op_sel_hi:[1,0]
	v_pk_add_f32 v[252:253], v[252:253], 1.0 op_sel_hi:[1,0]
	v_rcp_f32_e32 v250, v250
	v_rcp_f32_e32 v251, v251
	v_rcp_f32_e32 v252, v252
	v_rcp_f32_e32 v253, v253
	v_pk_fma_f32 v[250:251], v[248:249], v[250:251], v[248:249] neg_lo:[1,0,0] neg_hi:[1,0,0]
	v_pk_fma_f32 v[252:253], v[236:237], v[252:253], v[236:237] neg_lo:[1,0,0] neg_hi:[1,0,0]
	v_pk_mul_f32 v[250:251], v[16:17], v[250:251]
	v_pk_mul_f32 v[252:253], v[18:19], v[252:253]
	v_cvt_pk_bf16_f32 v248, v250, v251
	v_cvt_pk_bf16_f32 v249, v252, v253
	ds_write_b64 v223, v[248:249] offset:40960
	v_lshlrev_b32_e32 v236, 16, v188
	v_and_b32_e32 v237, 0xffff0000, v188
	v_lshlrev_b32_e32 v238, 16, v189
	v_and_b32_e32 v239, 0xffff0000, v189
	v_lshlrev_b32_e32 v240, 16, v186
	v_and_b32_e32 v241, 0xffff0000, v186
	v_lshlrev_b32_e32 v242, 16, v187
	v_and_b32_e32 v243, 0xffff0000, v187
	v_lshlrev_b32_e32 v244, 16, v190
	v_and_b32_e32 v245, 0xffff0000, v190
	v_lshlrev_b32_e32 v246, 16, v191
	v_and_b32_e32 v247, 0xffff0000, v191
	v_pk_mul_f32 v[236:237], v[236:237], v[128:129]
	v_pk_mul_f32 v[238:239], v[238:239], v[130:131]
	v_pk_fma_f32 v[248:249], v[132:133], v[240:241], v[236:237]
	v_pk_fma_f32 v[236:237], v[134:135], v[242:243], v[238:239]
; #define PUT(val) *(uint2*)(g_smem + est_off(rl_, cl)) = pack4(val)
; #define STAGED2(WBODY, SBODY) { { constexpr int AIV = 0; (void)AIV; HLOOP(0, WBODY) __syncthreads(); WLOOP(0, SBODY) } __syncthreads(); { constexpr int AIV = 1; (void)AIV; HLOOP(1, WBODY) __syncthreads(); WLOOP(1, SBODY) } }
; __device__ __forceinline__ float gelu_tanh(float x) {
;   float u = 0.7978845608028654f * (x + 0.044715f * x * x * x);
;   float e = __expf(2.f * u);
;   float t = 1.f - 2.f * __builtin_amdgcn_rcpf(e + 1.f);
;   return 0.5f * x * (1.f + t);
; }
; __device__ __forceinline__ void gemm_epi(const Job& J, f32x4 (&acc)[2][2][4][2], int brow, int bcol, int wvs) {
;     ...
;     STAGED2(({ int pos = R & ((1 << lg) - 1); const u16* gp = G + (long)R * DFF + Cc;
;         f32x4 g0 = unpack4(*(const uint2*)gp), gm = {0.f, 0.f, 0.f, 0.f}, gn = {0.f, 0.f, 0.f, 0.f};
;         if (pos > 0) gm = unpack4(*(const uint2*)(gp - DFF));
;         if (pos < (1 << lg) - 1) gn = unpack4(*(const uint2*)(gp + DFF));
;         f32x4 w0 = *(const f32x4*)(cw + Cc), w1 = *(const f32x4*)(cw + DFF + Cc), w2 = *(const f32x4*)(cw + 2 * DFF + Cc), bb = *(const f32x4*)(cb + Cc);
;         f32x4 o; _Pragma("unroll") for (int j = 0; j < 4; ++j) { float cv = gm[j] * w0[j] + g0[j] * w1[j] + gn[j] * w2[j] + bb[j]; o[j] = gelu_tanh(cv) * v[j]; }
;         PUT(o); }), ({ *(u32x4*)(C + (long)R * ldc + Cc) = LDV; })) } break;
	v_pk_fma_f32 v[248:249], v[244:245], v[136:137], v[248:249]
	v_pk_fma_f32 v[236:237], v[246:247], v[138:139], v[236:237]
	v_pk_add_f32 v[248:249], v[140:141], v[248:249]
	v_pk_add_f32 v[236:237], v[142:143], v[236:237]
	v_pk_mul_f32 v[250:251], v[248:249], v[248:249]
	v_pk_mul_f32 v[252:253], v[236:237], v[236:237]
	v_pk_fma_f32 v[250:251], v[250:251], s[96:97], v[232:233] op_sel_hi:[1,0,1]
	v_pk_fma_f32 v[252:253], v[252:253], s[96:97], v[232:233] op_sel_hi:[1,0,1]
	v_pk_mul_f32 v[250:251], v[248:249], v[250:251]
	v_pk_mul_f32 v[252:253], v[236:237], v[252:253]
	v_exp_f32_e32 v250, v250
	v_exp_f32_e32 v251, v251
	v_exp_f32_e32 v252, v252
	v_exp_f32_e32 v253, v253
	v_pk_add_f32 v[250:251], v[250:251], 1.0 op_sel_hi:[1,0]
	v_pk_add_f32 v[252:253], v[252:253], 1.0 op_sel_hi:[1,0]
	v_rcp_f32_e32 v250, v250
	v_rcp_f32_e32 v251, v251
	v_rcp_f32_e32 v252, v252
	v_rcp_f32_e32 v253, v253
	v_pk_fma_f32 v[250:251], v[248:249], v[250:251], v[248:249] neg_lo:[1,0,0] neg_hi:[1,0,0]
	v_pk_fma_f32 v[252:253], v[236:237], v[252:253], v[236:237] neg_lo:[1,0,0] neg_hi:[1,0,0]
	v_pk_mul_f32 v[250:251], v[12:13], v[250:251]
	v_pk_mul_f32 v[252:253], v[14:15], v[252:253]
	v_cvt_pk_bf16_f32 v248, v250, v251
	v_cvt_pk_bf16_f32 v249, v252, v253
	ds_write_b64 v222, v[248:249] offset:49408
	v_lshlrev_b32_e32 v236, 16, v194
	v_and_b32_e32 v237, 0xffff0000, v194
	v_lshlrev_b32_e32 v238, 16, v195
	v_and_b32_e32 v239, 0xffff0000, v195
	v_lshlrev_b32_e32 v240, 16, v192
	v_and_b32_e32 v241, 0xffff0000, v192
	v_lshlrev_b32_e32 v242, 16, v193
	v_and_b32_e32 v243, 0xffff0000, v193
	v_lshlrev_b32_e32 v244, 16, v196
	v_and_b32_e32 v245, 0xffff0000, v196
	v_lshlrev_b32_e32 v246, 16, v197
	v_and_b32_e32 v247, 0xffff0000, v197
	v_pk_mul_f32 v[236:237], v[236:237], v[144:145]
	v_pk_mul_f32 v[238:239], v[238:239], v[146:147]
	v_pk_fma_f32 v[248:249], v[148:149], v[240:241], v[236:237]
	v_pk_fma_f32 v[236:237], v[150:151], v[242:243], v[238:239]
	v_pk_fma_f32 v[248:249], v[244:245], v[152:153], v[248:249]
	v_pk_fma_f32 v[236:237], v[246:247], v[154:155], v[236:237]
	v_pk_add_f32 v[248:249], v[156:157], v[248:249]
	v_pk_add_f32 v[236:237], v[158:159], v[236:237]
	v_pk_mul_f32 v[250:251], v[248:249], v[248:249]
	v_pk_mul_f32 v[252:253], v[236:237], v[236:237]
	v_pk_fma_f32 v[250:251], v[250:251], s[96:97], v[232:233] op_sel_hi:[1,0,1]
	v_pk_fma_f32 v[252:253], v[252:253], s[96:97], v[232:233] op_sel_hi:[1,0,1]
	v_pk_mul_f32 v[250:251], v[248:249], v[250:251]
	v_pk_mul_f32 v[252:253], v[236:237], v[252:253]
	v_exp_f32_e32 v250, v250
	v_exp_f32_e32 v251, v251
	v_exp_f32_e32 v252, v252
	v_exp_f32_e32 v253, v253
	v_pk_add_f32 v[250:251], v[250:251], 1.0 op_sel_hi:[1,0]
	v_pk_add_f32 v[252:253], v[252:253], 1.0 op_sel_hi:[1,0]
	v_rcp_f32_e32 v250, v250
	v_rcp_f32_e32 v251, v251
	v_rcp_f32_e32 v252, v252
	v_rcp_f32_e32 v253, v253
	v_pk_fma_f32 v[250:251], v[248:249], v[250:251], v[248:249] neg_lo:[1,0,0] neg_hi:[1,0,0]
	v_pk_fma_f32 v[252:253], v[236:237], v[252:253], v[236:237] neg_lo:[1,0,0] neg_hi:[1,0,0]
	v_pk_mul_f32 v[250:251], v[8:9], v[250:251]
	v_pk_mul_f32 v[252:253], v[10:11], v[252:253]
	v_cvt_pk_bf16_f32 v248, v250, v251
	v_cvt_pk_bf16_f32 v249, v252, v253
	ds_write_b64 v223, v[248:249] offset:49408
	v_add_u32_e32 v228, 176, v224
	v_and_b32_e32 v228, s31, v228
	v_cmp_ne_u32_e32 vcc, s31, v228
	s_nop 1
	v_cndmask_b32_e64 v226, 0, -1, vcc
	v_and_b32_e32 v202, v226, v202
	v_and_b32_e32 v203, v226, v203
	v_lshlrev_b32_e32 v236, 16, v200
	v_and_b32_e32 v237, 0xffff0000, v200
	v_lshlrev_b32_e32 v238, 16, v201
	v_and_b32_e32 v239, 0xffff0000, v201
	v_lshlrev_b32_e32 v240, 16, v198
	v_and_b32_e32 v241, 0xffff0000, v198
	v_lshlrev_b32_e32 v242, 16, v199
	v_and_b32_e32 v243, 0xffff0000, v199
	v_lshlrev_b32_e32 v244, 16, v202
	v_and_b32_e32 v245, 0xffff0000, v202
	v_lshlrev_b32_e32 v246, 16, v203
	v_and_b32_e32 v247, 0xffff0000, v203
	v_pk_mul_f32 v[236:237], v[236:237], v[128:129]
	v_pk_mul_f32 v[238:239], v[238:239], v[130:131]
	v_pk_fma_f32 v[248:249], v[132:133], v[240:241], v[236:237]
	v_pk_fma_f32 v[236:237], v[134:135], v[242:243], v[238:239]
	v_pk_fma_f32 v[248:249], v[244:245], v[136:137], v[248:249]
	v_pk_fma_f32 v[236:237], v[246:247], v[138:139], v[236:237]
	v_pk_add_f32 v[248:249], v[140:141], v[248:249]
	v_pk_add_f32 v[236:237], v[142:143], v[236:237]
	v_pk_mul_f32 v[250:251], v[248:249], v[248:249]
	v_pk_mul_f32 v[252:253], v[236:237], v[236:237]
	v_pk_fma_f32 v[250:251], v[250:251], s[96:97], v[232:233] op_sel_hi:[1,0,1]
	v_pk_fma_f32 v[252:253], v[252:253], s[96:97], v[232:233] op_sel_hi:[1,0,1]
; #define PUT(val) *(uint2*)(g_smem + est_off(rl_, cl)) = pack4(val)
; #define STAGED2(WBODY, SBODY) { { constexpr int AIV = 0; (void)AIV; HLOOP(0, WBODY) __syncthreads(); WLOOP(0, SBODY) } __syncthreads(); { constexpr int AIV = 1; (void)AIV; HLOOP(1, WBODY) __syncthreads(); WLOOP(1, SBODY) } }
; __device__ __forceinline__ void gemm_epi(const Job& J, f32x4 (&acc)[2][2][4][2], int brow, int bcol, int wvs) {
;     ...
;   switch (mode) {
;   case E_UPACT: { u16* C = (u16*)J.C; const u16* G = (const u16*)J.aux; const float* cw = (const float*)J.aux2; const float* cb = (const float*)J.aux3; const int lg = J.flag;
;     STAGED2(({ int pos = R & ((1 << lg) - 1); const u16* gp = G + (long)R * DFF + Cc;
;         f32x4 g0 = unpack4(*(const uint2*)gp), gm = {0.f, 0.f, 0.f, 0.f}, gn = {0.f, 0.f, 0.f, 0.f};
;         if (pos > 0) gm = unpack4(*(const uint2*)(gp - DFF));
;         if (pos < (1 << lg) - 1) gn = unpack4(*(const uint2*)(gp + DFF));
;         f32x4 w0 = *(const f32x4*)(cw + Cc), w1 = *(const f32x4*)(cw + DFF + Cc), w2 = *(const f32x4*)(cw + 2 * DFF + Cc), bb = *(const f32x4*)(cb + Cc);
;         f32x4 o; _Pragma("unroll") for (int j = 0; j < 4; ++j) { float cv = gm[j] * w0[j] + g0[j] * w1[j] + gn[j] * w2[j] + bb[j]; o[j] = gelu_tanh(cv) * v[j]; }
;         PUT(o); }), ({ *(u32x4*)(C + (long)R * ldc + Cc) = LDV; })) } break;
	v_pk_mul_f32 v[250:251], v[248:249], v[250:251]
	v_pk_mul_f32 v[252:253], v[236:237], v[252:253]
	v_exp_f32_e32 v250, v250
	v_exp_f32_e32 v251, v251
	v_exp_f32_e32 v252, v252
	v_exp_f32_e32 v253, v253
	v_pk_add_f32 v[250:251], v[250:251], 1.0 op_sel_hi:[1,0]
	v_pk_add_f32 v[252:253], v[252:253], 1.0 op_sel_hi:[1,0]
	v_rcp_f32_e32 v250, v250
	v_rcp_f32_e32 v251, v251
	v_rcp_f32_e32 v252, v252
	v_rcp_f32_e32 v253, v253
	v_pk_fma_f32 v[250:251], v[248:249], v[250:251], v[248:249] neg_lo:[1,0,0] neg_hi:[1,0,0]
	v_pk_fma_f32 v[252:253], v[236:237], v[252:253], v[236:237] neg_lo:[1,0,0] neg_hi:[1,0,0]
	v_pk_mul_f32 v[250:251], v[4:5], v[250:251]
	v_pk_mul_f32 v[252:253], v[6:7], v[252:253]
	v_cvt_pk_bf16_f32 v248, v250, v251
	v_cvt_pk_bf16_f32 v249, v252, v253
	ds_write_b64 v222, v[248:249] offset:57344
	v_and_b32_e32 v218, v226, v218
	v_and_b32_e32 v219, v226, v219
	v_lshlrev_b32_e32 v236, 16, v216
	v_and_b32_e32 v237, 0xffff0000, v216
	v_lshlrev_b32_e32 v238, 16, v217
	v_and_b32_e32 v239, 0xffff0000, v217
	v_lshlrev_b32_e32 v240, 16, v214
	v_and_b32_e32 v241, 0xffff0000, v214
	v_lshlrev_b32_e32 v242, 16, v215
	v_and_b32_e32 v243, 0xffff0000, v215
	v_lshlrev_b32_e32 v244, 16, v218
	v_and_b32_e32 v245, 0xffff0000, v218
	v_lshlrev_b32_e32 v246, 16, v219
	v_and_b32_e32 v247, 0xffff0000, v219
	v_pk_mul_f32 v[236:237], v[236:237], v[144:145]
	v_pk_mul_f32 v[238:239], v[238:239], v[146:147]
	v_pk_fma_f32 v[248:249], v[148:149], v[240:241], v[236:237]
	v_pk_fma_f32 v[236:237], v[150:151], v[242:243], v[238:239]
	v_pk_fma_f32 v[248:249], v[244:245], v[152:153], v[248:249]
	v_pk_fma_f32 v[236:237], v[246:247], v[154:155], v[236:237]
	v_pk_add_f32 v[248:249], v[156:157], v[248:249]
	v_pk_add_f32 v[236:237], v[158:159], v[236:237]
	v_pk_mul_f32 v[250:251], v[248:249], v[248:249]
	v_pk_mul_f32 v[252:253], v[236:237], v[236:237]
	v_pk_fma_f32 v[250:251], v[250:251], s[96:97], v[232:233] op_sel_hi:[1,0,1]
	v_pk_fma_f32 v[252:253], v[252:253], s[96:97], v[232:233] op_sel_hi:[1,0,1]
	v_pk_mul_f32 v[250:251], v[248:249], v[250:251]
	v_pk_mul_f32 v[252:253], v[236:237], v[252:253]
	v_exp_f32_e32 v250, v250
	v_exp_f32_e32 v251, v251
	v_exp_f32_e32 v252, v252
	v_exp_f32_e32 v253, v253
	v_pk_add_f32 v[250:251], v[250:251], 1.0 op_sel_hi:[1,0]
	v_pk_add_f32 v[252:253], v[252:253], 1.0 op_sel_hi:[1,0]
	v_rcp_f32_e32 v250, v250
	v_rcp_f32_e32 v251, v251
	v_rcp_f32_e32 v252, v252
	v_rcp_f32_e32 v253, v253
	v_pk_fma_f32 v[250:251], v[248:249], v[250:251], v[248:249] neg_lo:[1,0,0] neg_hi:[1,0,0]
	v_pk_fma_f32 v[252:253], v[236:237], v[252:253], v[236:237] neg_lo:[1,0,0] neg_hi:[1,0,0]
	v_pk_mul_f32 v[250:251], v[0:1], v[250:251]
	v_pk_mul_f32 v[252:253], v[2:3], v[252:253]
	v_cvt_pk_bf16_f32 v248, v250, v251
	v_cvt_pk_bf16_f32 v249, v252, v253
	ds_write_b64 v223, v[248:249] offset:57344
	s_waitcnt lgkmcnt(0)
	s_barrier
	v_add_u32_e32 v99, s69, v210
	v_lshrrev_b32_e32 v99, 5, v99
	v_and_b32_e32 v98, 31, v210
	v_xor_b32_e32 v96, v98, v99
	v_lshlrev_b32_e32 v96, 4, v96
	v_xor_b32_e32 v97, 0x100, v96
	v_lshl_add_u32 v96, v99, 9, v96
	v_lshl_add_u32 v97, v99, 9, v97
	v_mul_u32_u24_e32 v99, s4, v99
	v_lshlrev_b32_e32 v98, 4, v98
	v_lshl_add_u32 v98, v99, 1, v98
	s_mul_i32 s6, s84, s4
	s_add_i32 s6, s6, s22
	s_lshl_b32 s6, s6, 1
	s_add_u32 s6, s26, s6
	s_addc_u32 s7, s27, 0
	s_lshl_b32 s8, s4, 5
	ds_read_b128 v[64:67], v96 offset:32768
	ds_read_b128 v[68:71], v97 offset:40960
	ds_read_b128 v[72:75], v96 offset:49152
	ds_read_b128 v[76:79], v97 offset:57344
	v_add_u32_e32 v96, 0x10000, v96
	v_add_u32_e32 v97, 0x10000, v97
	ds_read_b128 v[80:83], v96 offset:32768
	ds_read_b128 v[84:87], v97 offset:40960
	ds_read_b128 v[88:91], v96 offset:49152
	ds_read_b128 v[92:95], v97 offset:57344
	s_waitcnt lgkmcnt(7)
	global_store_dwordx4 v98, v[64:67], s[6:7]
	s_add_u32 s6, s6, s8
	s_addc_u32 s7, s7, 0
	s_waitcnt lgkmcnt(6)
	global_store_dwordx4 v98, v[68:71], s[6:7]
	s_add_u32 s6, s6, s8
	s_addc_u32 s7, s7, 0
	s_waitcnt lgkmcnt(5)
	global_store_dwordx4 v98, v[72:75], s[6:7]
	s_add_u32 s6, s6, s8
	s_addc_u32 s7, s7, 0
	s_waitcnt lgkmcnt(4)
	global_store_dwordx4 v98, v[76:79], s[6:7]
	s_add_u32 s6, s6, s8
	s_addc_u32 s7, s7, 0
	s_waitcnt lgkmcnt(3)
	global_store_dwordx4 v98, v[80:83], s[6:7]
	s_add_u32 s6, s6, s8
	s_addc_u32 s7, s7, 0
	s_waitcnt lgkmcnt(2)
	global_store_dwordx4 v98, v[84:87], s[6:7]
	s_add_u32 s6, s6, s8
	s_addc_u32 s7, s7, 0
	s_waitcnt lgkmcnt(1)
	global_store_dwordx4 v98, v[88:91], s[6:7]
	s_add_u32 s6, s6, s8
	s_addc_u32 s7, s7, 0
	s_waitcnt lgkmcnt(0)
	global_store_dwordx4 v98, v[92:95], s[6:7]
	s_mov_b64 s[8:9], 0

; #define PUT(val) *(uint2*)(g_smem + est_off(rl_, cl)) = pack4(val)
; #define STAGED2(WBODY, SBODY) { { constexpr int AIV = 0; (void)AIV; HLOOP(0, WBODY) __syncthreads(); WLOOP(0, SBODY) } __syncthreads(); { constexpr int AIV = 1; (void)AIV; HLOOP(1, WBODY) __syncthreads(); WLOOP(1, SBODY) } }
; __device__ __forceinline__ void gemm_epi(const Job& J, f32x4 (&acc)[2][2][4][2], int brow, int bcol, int wvs) {
;     ...
;   default: { u16* C = (u16*)J.C; STAGED2(({ v *= sc; PUT(v); }), ({ *(u32x4*)(C + (long)R * ldc + Cc) = LDV; })) } break;
.LBB0_760:
	v_add_u32_e32 v99, s69, v210
	v_lshrrev_b32_e32 v99, 5, v99
	v_and_b32_e32 v98, 31, v210
	v_xor_b32_e32 v96, v98, v99
	v_lshlrev_b32_e32 v96, 4, v96
	v_xor_b32_e32 v97, 0x100, v96
	v_lshl_add_u32 v96, v99, 9, v96
	v_lshl_add_u32 v97, v99, 9, v97
	v_mul_u32_u24_e32 v99, s4, v99
	v_lshlrev_b32_e32 v98, 4, v98
	v_lshl_add_u32 v98, v99, 1, v98
	s_mul_i32 s8, s90, s4
	s_add_i32 s8, s8, s22
	s_lshl_b32 s8, s8, 1
	s_add_u32 s8, s26, s8
	s_addc_u32 s9, s27, 0
	s_lshl_b32 s10, s4, 5
	ds_read_b128 v[64:67], v96 offset:32768
	ds_read_b128 v[68:71], v97 offset:40960
	ds_read_b128 v[72:75], v96 offset:49152
	ds_read_b128 v[76:79], v97 offset:57344
	v_add_u32_e32 v96, 0x10000, v96
	v_add_u32_e32 v97, 0x10000, v97
	ds_read_b128 v[80:83], v96 offset:32768
	ds_read_b128 v[84:87], v97 offset:40960
	ds_read_b128 v[88:91], v96 offset:49152
	ds_read_b128 v[92:95], v97 offset:57344
	s_waitcnt lgkmcnt(7)
	global_store_dwordx4 v98, v[64:67], s[8:9]
	s_add_u32 s8, s8, s10
	s_addc_u32 s9, s9, 0
	s_waitcnt lgkmcnt(6)
	global_store_dwordx4 v98, v[68:71], s[8:9]
	s_add_u32 s8, s8, s10
	s_addc_u32 s9, s9, 0
	s_waitcnt lgkmcnt(5)
	global_store_dwordx4 v98, v[72:75], s[8:9]
	s_add_u32 s8, s8, s10
	s_addc_u32 s9, s9, 0
	s_waitcnt lgkmcnt(4)
	global_store_dwordx4 v98, v[76:79], s[8:9]
	s_add_u32 s8, s8, s10
	s_addc_u32 s9, s9, 0
	s_waitcnt lgkmcnt(3)
	global_store_dwordx4 v98, v[80:83], s[8:9]
	s_add_u32 s8, s8, s10
	s_addc_u32 s9, s9, 0
	s_waitcnt lgkmcnt(2)
	global_store_dwordx4 v98, v[84:87], s[8:9]
	s_add_u32 s8, s8, s10
	s_addc_u32 s9, s9, 0
	s_waitcnt lgkmcnt(1)
	global_store_dwordx4 v98, v[88:91], s[8:9]
	s_add_u32 s8, s8, s10
	s_addc_u32 s9, s9, 0
	s_waitcnt lgkmcnt(0)
	global_store_dwordx4 v98, v[92:95], s[8:9]
	s_nop 0
	v_pk_mul_f32 v[144:145], v[62:63], s[6:7]
	v_pk_mul_f32 v[146:147], v[60:61], s[30:31]
	s_waitcnt lgkmcnt(0)
	v_cvt_pk_bf16_f32 v146, v146, v147
	v_cvt_pk_bf16_f32 v147, v144, v145
	s_barrier
	ds_write_b64 v131, v[146:147] offset:32768
	v_pk_mul_f32 v[144:145], v[58:59], s[6:7]
	v_pk_mul_f32 v[146:147], v[56:57], s[30:31]
	v_pk_mul_f32 v[148:149], v[52:53], s[30:31]
	v_cvt_pk_bf16_f32 v146, v146, v147
	v_cvt_pk_bf16_f32 v147, v144, v145
	v_pk_mul_f32 v[144:145], v[54:55], s[6:7]
	v_cvt_pk_bf16_f32 v148, v148, v149
	v_cvt_pk_bf16_f32 v149, v144, v145
	ds_write_b64 v135, v[148:149] offset:32768
	v_pk_mul_f32 v[144:145], v[50:51], s[6:7]
	v_pk_mul_f32 v[148:149], v[48:49], s[30:31]
	s_mov_b32 s8, s69
	v_cvt_pk_bf16_f32 v148, v148, v149
	v_cvt_pk_bf16_f32 v149, v144, v145
	ds_write_b64 v136, v[148:149] offset:32768
	v_pk_mul_f32 v[144:145], v[46:47], s[6:7]
	v_pk_mul_f32 v[148:149], v[44:45], s[30:31]
	s_nop 0
	v_cvt_pk_bf16_f32 v148, v148, v149
	v_cvt_pk_bf16_f32 v149, v144, v145
	ds_write_b64 v131, v[148:149] offset:49152
	v_pk_mul_f32 v[144:145], v[42:43], s[6:7]
	v_pk_mul_f32 v[148:149], v[40:41], s[30:31]
	s_nop 0
	v_cvt_pk_bf16_f32 v148, v148, v149
	v_cvt_pk_bf16_f32 v149, v144, v145
	ds_write2st64_b64 v132, v[146:147], v[148:149] offset0:64 offset1:96
	v_pk_mul_f32 v[144:145], v[38:39], s[6:7]
	v_pk_mul_f32 v[146:147], v[36:37], s[30:31]
	s_nop 0
	v_cvt_pk_bf16_f32 v146, v146, v147
	v_cvt_pk_bf16_f32 v147, v144, v145
	ds_write_b64 v137, v[146:147] offset:32768
	v_pk_mul_f32 v[136:137], v[34:35], s[6:7]
	v_pk_mul_f32 v[144:145], v[32:33], s[30:31]
	v_pk_mul_f32 v[146:147], v[20:21], s[30:31]
	v_cvt_pk_bf16_f32 v144, v144, v145
	v_cvt_pk_bf16_f32 v145, v136, v137
	ds_write_b64 v138, v[144:145] offset:32768
	v_pk_mul_f32 v[136:137], v[30:31], s[6:7]
	v_pk_mul_f32 v[144:145], v[28:29], s[30:31]
	v_cvt_pk_bf16_f32 v146, v146, v147
	v_cvt_pk_bf16_f32 v144, v144, v145
	v_cvt_pk_bf16_f32 v145, v136, v137
	ds_write_b64 v133, v[144:145] offset:32768
	v_pk_mul_f32 v[136:137], v[26:27], s[6:7]
	v_pk_mul_f32 v[144:145], v[24:25], s[30:31]
	s_nop 0
	v_cvt_pk_bf16_f32 v144, v144, v145
	v_cvt_pk_bf16_f32 v145, v136, v137
	v_pk_mul_f32 v[136:137], v[22:23], s[6:7]
	s_nop 0
	v_cvt_pk_bf16_f32 v147, v136, v137
	ds_write_b64 v139, v[146:147] offset:32768
	v_pk_mul_f32 v[136:137], v[18:19], s[6:7]
	v_pk_mul_f32 v[138:139], v[16:17], s[30:31]
	s_nop 0
	v_cvt_pk_bf16_f32 v138, v138, v139
	v_cvt_pk_bf16_f32 v139, v136, v137
	ds_write_b64 v140, v[138:139] offset:32768
	v_pk_mul_f32 v[136:137], v[14:15], s[6:7]
	v_pk_mul_f32 v[138:139], v[12:13], s[30:31]
	s_nop 0
	v_cvt_pk_bf16_f32 v138, v138, v139
	v_cvt_pk_bf16_f32 v139, v136, v137
	ds_write_b64 v133, v[138:139] offset:49152
	v_pk_mul_f32 v[132:133], v[10:11], s[6:7]
	v_pk_mul_f32 v[136:137], v[8:9], s[30:31]
	s_nop 0
	v_cvt_pk_bf16_f32 v136, v136, v137
	v_cvt_pk_bf16_f32 v137, v132, v133
	ds_write2st64_b64 v134, v[144:145], v[136:137] offset0:64 offset1:96
	v_pk_mul_f32 v[132:133], v[6:7], s[6:7]
	v_pk_mul_f32 v[134:135], v[4:5], s[30:31]
	s_nop 0
	v_cvt_pk_bf16_f32 v134, v134, v135
	v_cvt_pk_bf16_f32 v135, v132, v133
	ds_write_b64 v141, v[134:135] offset:32768
	v_pk_mul_f32 v[132:133], v[2:3], s[6:7]
	v_pk_mul_f32 v[134:135], v[0:1], s[30:31]
	s_add_i32 s6, s90, 0x80
	v_cvt_pk_bf16_f32 v134, v134, v135
	v_cvt_pk_bf16_f32 v135, v132, v133
	s_mov_b32 s7, 8
	ds_write_b64 v142, v[134:135] offset:32768
	s_waitcnt lgkmcnt(0)
	s_barrier
.LBB0_762:
	v_add_u32_e32 v99, s69, v210
	v_lshrrev_b32_e32 v99, 5, v99
	v_and_b32_e32 v98, 31, v210
	v_xor_b32_e32 v96, v98, v99
	v_lshlrev_b32_e32 v96, 4, v96
	v_xor_b32_e32 v97, 0x100, v96
	v_lshl_add_u32 v96, v99, 9, v96
	v_lshl_add_u32 v97, v99, 9, v97
	v_mul_u32_u24_e32 v99, s4, v99
	v_lshlrev_b32_e32 v98, 4, v98
	v_lshl_add_u32 v98, v99, 1, v98
	s_mul_i32 s10, s6, s4
	s_add_i32 s10, s10, s22
	s_lshl_b32 s10, s10, 1
	s_add_u32 s10, s26, s10
	s_addc_u32 s11, s27, 0
	s_lshl_b32 s8, s4, 5
	ds_read_b128 v[64:67], v96 offset:32768
	ds_read_b128 v[68:71], v97 offset:40960
	ds_read_b128 v[72:75], v96 offset:49152
	ds_read_b128 v[76:79], v97 offset:57344
	v_add_u32_e32 v96, 0x10000, v96
	v_add_u32_e32 v97, 0x10000, v97
	ds_read_b128 v[80:83], v96 offset:32768
	ds_read_b128 v[84:87], v97 offset:40960
	ds_read_b128 v[88:91], v96 offset:49152
	ds_read_b128 v[92:95], v97 offset:57344
	s_waitcnt lgkmcnt(7)
	global_store_dwordx4 v98, v[64:67], s[10:11]
	s_add_u32 s10, s10, s8
	s_addc_u32 s11, s11, 0
	s_waitcnt lgkmcnt(6)
	global_store_dwordx4 v98, v[68:71], s[10:11]
	s_add_u32 s10, s10, s8
	s_addc_u32 s11, s11, 0
	s_waitcnt lgkmcnt(5)
	global_store_dwordx4 v98, v[72:75], s[10:11]
	s_add_u32 s10, s10, s8
	s_addc_u32 s11, s11, 0
	s_waitcnt lgkmcnt(4)
	global_store_dwordx4 v98, v[76:79], s[10:11]
	s_add_u32 s10, s10, s8
	s_addc_u32 s11, s11, 0
	s_waitcnt lgkmcnt(3)
	global_store_dwordx4 v98, v[80:83], s[10:11]
	s_add_u32 s10, s10, s8
	s_addc_u32 s11, s11, 0
	s_waitcnt lgkmcnt(2)
	global_store_dwordx4 v98, v[84:87], s[10:11]
	s_add_u32 s10, s10, s8
	s_addc_u32 s11, s11, 0
	s_waitcnt lgkmcnt(1)
	global_store_dwordx4 v98, v[88:91], s[10:11]
	s_add_u32 s10, s10, s8
	s_addc_u32 s11, s11, 0
	s_waitcnt lgkmcnt(0)
	global_store_dwordx4 v98, v[92:95], s[10:11]
	s_mov_b64 s[52:53], 0
